# GEMM K-loops: merged back-to-back s_setprio 0/1 pairs between the two MFMA blocks of a super-phase
# baseline (speedup 1.0000x reference)
; #define PG8_STAGE(bufoff, gbase, voff) do { _Pragma("unroll") for (int _i = 0; _i < 2; ++_i) \
;         __builtin_amdgcn_global_load_lds((const unsigned*)((const char*)(gbase) + (voff)[_i]), (PG8_LAS unsigned*)(lds + (bufoff) + ldsw + _i * 8192), 16, 0, 0); } while (0)
; #define PG8_LDA(dst, b, h) do { _Pragma("unroll") for (int m = 0; m < 4; ++m) _Pragma("unroll") for (int k = 0; k < 2; ++k) dst[m][k] = *(const PG8_LAS bf16x8*)(lds + PG8_SA(b, h) + aoff + m * 2048 + k * 1024); } while (0)
; #define PG8_LDB(dst, b, h) do { _Pragma("unroll") for (int n = 0; n < 2; ++n) _Pragma("unroll") for (int k = 0; k < 2; ++k) dst[n][k] = *(const PG8_LAS bf16x8*)(lds + PG8_SB(b, h) + boff + n * 2048 + k * 1024); } while (0)
; #define PG8_MMA(ai, bj, At, Bt) do { __builtin_amdgcn_s_setprio(1); _Pragma("unroll") for (int m = 0; m < 4; ++m) _Pragma("unroll") for (int n = 0; n < 2; ++n) _Pragma("unroll") for (int k = 0; k < 2; ++k) \
;         acc[ai][bj][m][n] = __builtin_amdgcn_mfma_f32_16x16x32_bf16(Bt[n][k], At[m][k], acc[ai][bj][m][n], 0, 0, 0); __builtin_amdgcn_s_setprio(0); } while (0)
; #define PG8_WAIT_V(n) asm volatile("s_waitcnt vmcnt(" #n ")" ::: "memory")
; #define PG8_WAIT_L(n) asm volatile("s_waitcnt lgkmcnt(" #n ")" ::: "memory")
; #define PG8_BAR __builtin_amdgcn_s_barrier()
; #define PG8_SCHED __builtin_amdgcn_sched_barrier(0)
; template <class Epi, class Sched, bool ALIGN_EPI = false, bool SP2 = false>
; __device__ __forceinline__ void gemm_phase(PG8_LAS unsigned char* lds, const Gemm g, const Sched& S, const Epi& E) {
;     ...
;             PG8_LDB(B0, 0, 0); PG8_LDB(B1, 0, 1); PG8_SCHED; PG8_LDA(At, 0, 0); PG8_STAGE(PG8_SA(1, 1), a1 + hstep, voffA);
;             PG8_WAIT_V(8); PG8_WAIT_L(0); PG8_BAR; PG8_MMA(0, 0, At, B0); PG8_MMA(0, 1, At, B1); PG8_BAR; PG8_SCHED;
;             PG8_LDA(At, 0, 1); PG8_STAGE(PG8_SB(0, 0), b2, voffB); PG8_STAGE(PG8_SB(0, 1), b2 + hstep, voffB); PG8_STAGE(PG8_SA(0, 0), a2, voffA);
.LBB0_86:
	ds_read_b128 v[128:131], v188
	ds_read_b128 v[132:135], v188 offset:1024
	ds_read_b128 v[136:139], v188 offset:2048
	ds_read_b128 v[140:143], v188 offset:3072
	ds_read_b128 v[168:171], v189
	ds_read_b128 v[172:175], v189 offset:1024
	ds_read_b128 v[176:179], v189 offset:2048
	ds_read_b128 v[180:183], v189 offset:3072
	s_add_u32 s72, s8, 0xfff00080
	s_addc_u32 s73, s9, -1
	s_cmp_eq_u32 s91, 60
	s_cselect_b32 s75, s7, s73
	s_cselect_b32 s74, s13, s72
	s_cselect_b32 s73, s16, s90
	s_cselect_b32 s72, s65, s67
	v_lshl_add_u64 v[184:185], s[8:9], 0, v[160:161]
	s_add_i32 m0, s63, 0xc000
	ds_read_b128 v[196:199], v190
	ds_read_b128 v[200:203], v190 offset:1024
	ds_read_b128 v[204:207], v190 offset:2048
	ds_read_b128 v[208:211], v190 offset:3072
	ds_read_b128 v[212:215], v190 offset:4096
	ds_read_b128 v[216:219], v190 offset:5120
	ds_read_b128 v[220:223], v190 offset:6144
	ds_read_b128 v[224:227], v190 offset:7168
	global_load_lds_dwordx4 v[184:185], off
	v_lshl_add_u64 v[184:185], s[8:9], 0, v[162:163]
	s_add_i32 m0, s63, 0xe000
	s_nop 0
	global_load_lds_dwordx4 v[184:185], off
	s_waitcnt vmcnt(8)
	s_waitcnt lgkmcnt(0)
	s_barrier
	s_setprio 1
	s_waitcnt lgkmcnt(0)
	v_mfma_f32_16x16x32_bf16 v[124:127], v[128:131], v[196:199], v[124:127]
	v_mfma_f32_16x16x32_bf16 v[120:123], v[136:139], v[196:199], v[120:123]
	v_mfma_f32_16x16x32_bf16 v[108:111], v[128:131], v[204:207], v[108:111]
	v_mfma_f32_16x16x32_bf16 v[104:107], v[136:139], v[204:207], v[104:107]
	v_mfma_f32_16x16x32_bf16 v[92:95], v[128:131], v[212:215], v[92:95]
	v_mfma_f32_16x16x32_bf16 v[88:91], v[136:139], v[212:215], v[88:91]
	v_mfma_f32_16x16x32_bf16 v[76:79], v[128:131], v[220:223], v[76:79]
	v_mfma_f32_16x16x32_bf16 v[72:75], v[136:139], v[220:223], v[72:75]
	v_mfma_f32_16x16x32_bf16 v[124:127], v[132:135], v[200:203], v[124:127]
	v_mfma_f32_16x16x32_bf16 v[120:123], v[140:143], v[200:203], v[120:123]
	v_mfma_f32_16x16x32_bf16 v[108:111], v[132:135], v[208:211], v[108:111]
	v_mfma_f32_16x16x32_bf16 v[104:107], v[140:143], v[208:211], v[104:107]
	v_mfma_f32_16x16x32_bf16 v[92:95], v[132:135], v[216:219], v[92:95]
	v_mfma_f32_16x16x32_bf16 v[88:91], v[140:143], v[216:219], v[88:91]
	v_mfma_f32_16x16x32_bf16 v[76:79], v[132:135], v[224:227], v[76:79]
	v_mfma_f32_16x16x32_bf16 v[72:75], v[140:143], v[224:227], v[72:75]
	v_mfma_f32_16x16x32_bf16 v[116:119], v[168:171], v[196:199], v[116:119]
	v_mfma_f32_16x16x32_bf16 v[112:115], v[176:179], v[196:199], v[112:115]
	v_mfma_f32_16x16x32_bf16 v[100:103], v[168:171], v[204:207], v[100:103]
	v_mfma_f32_16x16x32_bf16 v[96:99], v[176:179], v[204:207], v[96:99]
	v_mfma_f32_16x16x32_bf16 v[84:87], v[168:171], v[212:215], v[84:87]
	v_mfma_f32_16x16x32_bf16 v[80:83], v[176:179], v[212:215], v[80:83]
	v_mfma_f32_16x16x32_bf16 v[68:71], v[168:171], v[220:223], v[68:71]
	v_mfma_f32_16x16x32_bf16 v[64:67], v[176:179], v[220:223], v[64:67]
	v_mfma_f32_16x16x32_bf16 v[116:119], v[172:175], v[200:203], v[116:119]
	v_mfma_f32_16x16x32_bf16 v[112:115], v[180:183], v[200:203], v[112:115]
	v_mfma_f32_16x16x32_bf16 v[100:103], v[172:175], v[208:211], v[100:103]
	v_mfma_f32_16x16x32_bf16 v[96:99], v[180:183], v[208:211], v[96:99]
	v_mfma_f32_16x16x32_bf16 v[84:87], v[172:175], v[216:219], v[84:87]
	v_mfma_f32_16x16x32_bf16 v[80:83], v[180:183], v[216:219], v[80:83]
	v_mfma_f32_16x16x32_bf16 v[68:71], v[172:175], v[224:227], v[68:71]
	v_mfma_f32_16x16x32_bf16 v[64:67], v[180:183], v[224:227], v[64:67]
	s_setprio 0
	s_barrier
	s_add_i32 s92, s87, s61
	v_lshl_add_u64 v[184:185], s[72:73], 0, v[146:147]
	s_mov_b32 m0, s92
	ds_read_b128 v[196:199], v190 offset:16384
	ds_read_b128 v[200:203], v190 offset:17408
	ds_read_b128 v[204:207], v190 offset:18432
	ds_read_b128 v[208:211], v190 offset:19456
	ds_read_b128 v[212:215], v190 offset:20480
	ds_read_b128 v[216:219], v190 offset:21504
	ds_read_b128 v[220:223], v190 offset:22528
	ds_read_b128 v[224:227], v190 offset:23552
	global_load_lds_dwordx4 v[184:185], off
	s_add_i32 m0, s92, 0x2000
	s_add_u32 s92, s72, 0x100000
	v_lshl_add_u64 v[228:229], s[72:73], 0, v[150:151]
	s_addc_u32 s93, s73, 0
	s_add_i32 s94, s88, s61
	global_load_lds_dwordx4 v[228:229], off
	v_lshl_add_u64 v[230:231], s[92:93], 0, v[146:147]
	s_mov_b32 m0, s94
	v_lshl_add_u64 v[232:233], s[74:75], 0, v[148:149]
	global_load_lds_dwordx4 v[230:231], off
	v_lshl_add_u64 v[230:231], s[92:93], 0, v[150:151]
	s_add_i32 m0, s94, 0x2000
	s_nop 0
	global_load_lds_dwordx4 v[230:231], off
	v_lshl_add_u64 v[230:231], s[74:75], 0, v[144:145]
	s_mov_b32 m0, s63
	s_nop 0
	global_load_lds_dwordx4 v[230:231], off
	s_mov_b32 m0, s76
	s_nop 0
	global_load_lds_dwordx4 v[232:233], off
	s_waitcnt vmcnt(8)
	s_waitcnt lgkmcnt(0)
	s_barrier
; #define PG8_STAGE(bufoff, gbase, voff) do { _Pragma("unroll") for (int _i = 0; _i < 2; ++_i) \
;         __builtin_amdgcn_global_load_lds((const unsigned*)((const char*)(gbase) + (voff)[_i]), (PG8_LAS unsigned*)(lds + (bufoff) + ldsw + _i * 8192), 16, 0, 0); } while (0)
; #define PG8_LDA(dst, b, h) do { _Pragma("unroll") for (int m = 0; m < 4; ++m) _Pragma("unroll") for (int k = 0; k < 2; ++k) dst[m][k] = *(const PG8_LAS bf16x8*)(lds + PG8_SA(b, h) + aoff + m * 2048 + k * 1024); } while (0)
; #define PG8_LDB(dst, b, h) do { _Pragma("unroll") for (int n = 0; n < 2; ++n) _Pragma("unroll") for (int k = 0; k < 2; ++k) dst[n][k] = *(const PG8_LAS bf16x8*)(lds + PG8_SB(b, h) + boff + n * 2048 + k * 1024); } while (0)
; #define PG8_MMA(ai, bj, At, Bt) do { __builtin_amdgcn_s_setprio(1); _Pragma("unroll") for (int m = 0; m < 4; ++m) _Pragma("unroll") for (int n = 0; n < 2; ++n) _Pragma("unroll") for (int k = 0; k < 2; ++k) \
;         acc[ai][bj][m][n] = __builtin_amdgcn_mfma_f32_16x16x32_bf16(Bt[n][k], At[m][k], acc[ai][bj][m][n], 0, 0, 0); __builtin_amdgcn_s_setprio(0); } while (0)
; #define PG8_WAIT_V(n) asm volatile("s_waitcnt vmcnt(" #n ")" ::: "memory")
; #define PG8_WAIT_L(n) asm volatile("s_waitcnt lgkmcnt(" #n ")" ::: "memory")
; #define PG8_BAR __builtin_amdgcn_s_barrier()
; #define PG8_SCHED __builtin_amdgcn_sched_barrier(0)
; template <class Epi, class Sched, bool ALIGN_EPI = false, bool SP2 = false>
; __device__ __forceinline__ void gemm_phase(PG8_LAS unsigned char* lds, const Gemm g, const Sched& S, const Epi& E) {
;     ...
;             PG8_WAIT_V(8); PG8_WAIT_L(0); PG8_BAR; PG8_MMA(1, 0, At, B0); PG8_MMA(1, 1, At, B1); PG8_BAR; PG8_SCHED;
;             PG8_LDB(B0, 1, 0); PG8_LDB(B1, 1, 1); PG8_SCHED; PG8_LDA(At, 1, 0); PG8_STAGE(PG8_SA(0, 1), a2 + hstep, voffA);
;             PG8_WAIT_V(8); PG8_WAIT_L(0); PG8_BAR; PG8_MMA(0, 0, At, B0); PG8_MMA(0, 1, At, B1); PG8_BAR; PG8_SCHED;
	s_setprio 1
	s_waitcnt lgkmcnt(0)
	v_mfma_f32_16x16x32_bf16 v[60:63], v[128:131], v[196:199], v[60:63]
	v_mfma_f32_16x16x32_bf16 v[56:59], v[136:139], v[196:199], v[56:59]
	v_mfma_f32_16x16x32_bf16 v[44:47], v[128:131], v[204:207], v[44:47]
	v_mfma_f32_16x16x32_bf16 v[40:43], v[136:139], v[204:207], v[40:43]
	v_mfma_f32_16x16x32_bf16 v[28:31], v[128:131], v[212:215], v[28:31]
	v_mfma_f32_16x16x32_bf16 v[24:27], v[136:139], v[212:215], v[24:27]
	v_mfma_f32_16x16x32_bf16 v[12:15], v[128:131], v[220:223], v[12:15]
	v_mfma_f32_16x16x32_bf16 v[8:11], v[136:139], v[220:223], v[8:11]
	v_mfma_f32_16x16x32_bf16 v[60:63], v[132:135], v[200:203], v[60:63]
	v_mfma_f32_16x16x32_bf16 v[56:59], v[140:143], v[200:203], v[56:59]
	v_mfma_f32_16x16x32_bf16 v[44:47], v[132:135], v[208:211], v[44:47]
	v_mfma_f32_16x16x32_bf16 v[40:43], v[140:143], v[208:211], v[40:43]
	v_mfma_f32_16x16x32_bf16 v[28:31], v[132:135], v[216:219], v[28:31]
	v_mfma_f32_16x16x32_bf16 v[24:27], v[140:143], v[216:219], v[24:27]
	v_mfma_f32_16x16x32_bf16 v[12:15], v[132:135], v[224:227], v[12:15]
	v_mfma_f32_16x16x32_bf16 v[8:11], v[140:143], v[224:227], v[8:11]
	v_mfma_f32_16x16x32_bf16 v[52:55], v[168:171], v[196:199], v[52:55]
	v_mfma_f32_16x16x32_bf16 v[48:51], v[176:179], v[196:199], v[48:51]
	v_mfma_f32_16x16x32_bf16 v[36:39], v[168:171], v[204:207], v[36:39]
	v_mfma_f32_16x16x32_bf16 v[32:35], v[176:179], v[204:207], v[32:35]
	v_mfma_f32_16x16x32_bf16 v[20:23], v[168:171], v[212:215], v[20:23]
	v_mfma_f32_16x16x32_bf16 v[16:19], v[176:179], v[212:215], v[16:19]
	v_mfma_f32_16x16x32_bf16 v[4:7], v[168:171], v[220:223], v[4:7]
	v_mfma_f32_16x16x32_bf16 v[0:3], v[176:179], v[220:223], v[0:3]
	v_mfma_f32_16x16x32_bf16 v[52:55], v[172:175], v[200:203], v[52:55]
	v_mfma_f32_16x16x32_bf16 v[48:51], v[180:183], v[200:203], v[48:51]
	v_mfma_f32_16x16x32_bf16 v[36:39], v[172:175], v[208:211], v[36:39]
	v_mfma_f32_16x16x32_bf16 v[32:35], v[180:183], v[208:211], v[32:35]
	v_mfma_f32_16x16x32_bf16 v[20:23], v[172:175], v[216:219], v[20:23]
	v_mfma_f32_16x16x32_bf16 v[16:19], v[180:183], v[216:219], v[16:19]
	v_mfma_f32_16x16x32_bf16 v[4:7], v[172:175], v[224:227], v[4:7]
	v_mfma_f32_16x16x32_bf16 v[0:3], v[180:183], v[224:227], v[0:3]
	s_setprio 0
	s_barrier
	s_add_i32 s92, 0, 0x18000
	s_add_i32 s93, 0, 0x1c000
	v_add_u32_e32 v140, s92, v187
	v_add_u32_e32 v152, s93, v187
	ds_read_b128 v[128:131], v140
	ds_read_b128 v[132:135], v140 offset:1024
	ds_read_b128 v[136:139], v140 offset:2048
	ds_read_b128 v[140:143], v140 offset:3072
	ds_read_b128 v[168:171], v152
	ds_read_b128 v[172:175], v152 offset:1024
	ds_read_b128 v[176:179], v152 offset:2048
	ds_read_b128 v[180:183], v152 offset:3072
	s_add_u32 s74, s74, 0x100000
	s_addc_u32 s75, s75, 0
	s_mov_b32 m0, s77
	v_lshl_add_u64 v[234:235], s[74:75], 0, v[144:145]
	ds_read_b128 v[196:199], v190 offset:32768
	ds_read_b128 v[200:203], v190 offset:33792
	ds_read_b128 v[204:207], v190 offset:34816
	ds_read_b128 v[208:211], v190 offset:35840
	ds_read_b128 v[212:215], v190 offset:36864
	ds_read_b128 v[216:219], v190 offset:37888
	ds_read_b128 v[220:223], v190 offset:38912
	ds_read_b128 v[224:227], v190 offset:39936
	global_load_lds_dwordx4 v[234:235], off
	v_lshl_add_u64 v[234:235], s[74:75], 0, v[148:149]
	s_mov_b32 m0, s78
	s_nop 0
	global_load_lds_dwordx4 v[234:235], off
	s_waitcnt vmcnt(8)
	s_waitcnt lgkmcnt(0)
	s_barrier
	s_setprio 1
	s_waitcnt lgkmcnt(0)
	v_mfma_f32_16x16x32_bf16 v[124:127], v[128:131], v[196:199], v[124:127]
	v_mfma_f32_16x16x32_bf16 v[120:123], v[136:139], v[196:199], v[120:123]
	v_mfma_f32_16x16x32_bf16 v[108:111], v[128:131], v[204:207], v[108:111]
	v_mfma_f32_16x16x32_bf16 v[104:107], v[136:139], v[204:207], v[104:107]
	v_mfma_f32_16x16x32_bf16 v[92:95], v[128:131], v[212:215], v[92:95]
	v_mfma_f32_16x16x32_bf16 v[88:91], v[136:139], v[212:215], v[88:91]
	v_mfma_f32_16x16x32_bf16 v[76:79], v[128:131], v[220:223], v[76:79]
	v_mfma_f32_16x16x32_bf16 v[72:75], v[136:139], v[220:223], v[72:75]
	v_mfma_f32_16x16x32_bf16 v[124:127], v[132:135], v[200:203], v[124:127]
	v_mfma_f32_16x16x32_bf16 v[120:123], v[140:143], v[200:203], v[120:123]
	v_mfma_f32_16x16x32_bf16 v[108:111], v[132:135], v[208:211], v[108:111]
	v_mfma_f32_16x16x32_bf16 v[104:107], v[140:143], v[208:211], v[104:107]
	v_mfma_f32_16x16x32_bf16 v[92:95], v[132:135], v[216:219], v[92:95]
	v_mfma_f32_16x16x32_bf16 v[88:91], v[140:143], v[216:219], v[88:91]
	v_mfma_f32_16x16x32_bf16 v[76:79], v[132:135], v[224:227], v[76:79]
	v_mfma_f32_16x16x32_bf16 v[72:75], v[140:143], v[224:227], v[72:75]
	v_mfma_f32_16x16x32_bf16 v[116:119], v[168:171], v[196:199], v[116:119]
	v_mfma_f32_16x16x32_bf16 v[112:115], v[176:179], v[196:199], v[112:115]
	v_mfma_f32_16x16x32_bf16 v[100:103], v[168:171], v[204:207], v[100:103]
	v_mfma_f32_16x16x32_bf16 v[96:99], v[176:179], v[204:207], v[96:99]
	v_mfma_f32_16x16x32_bf16 v[84:87], v[168:171], v[212:215], v[84:87]
	v_mfma_f32_16x16x32_bf16 v[80:83], v[176:179], v[212:215], v[80:83]
	v_mfma_f32_16x16x32_bf16 v[68:71], v[168:171], v[220:223], v[68:71]
	v_mfma_f32_16x16x32_bf16 v[64:67], v[176:179], v[220:223], v[64:67]
	v_mfma_f32_16x16x32_bf16 v[116:119], v[172:175], v[200:203], v[116:119]
	v_mfma_f32_16x16x32_bf16 v[112:115], v[180:183], v[200:203], v[112:115]
	v_mfma_f32_16x16x32_bf16 v[100:103], v[172:175], v[208:211], v[100:103]
	v_mfma_f32_16x16x32_bf16 v[96:99], v[180:183], v[208:211], v[96:99]
	v_mfma_f32_16x16x32_bf16 v[84:87], v[172:175], v[216:219], v[84:87]
	v_mfma_f32_16x16x32_bf16 v[80:83], v[180:183], v[216:219], v[80:83]
	v_mfma_f32_16x16x32_bf16 v[68:71], v[172:175], v[224:227], v[68:71]
	v_mfma_f32_16x16x32_bf16 v[64:67], v[180:183], v[224:227], v[64:67]
	s_setprio 0
	s_barrier
; #define PG8_STAGE(bufoff, gbase, voff) do { _Pragma("unroll") for (int _i = 0; _i < 2; ++_i) \
;         __builtin_amdgcn_global_load_lds((const unsigned*)((const char*)(gbase) + (voff)[_i]), (PG8_LAS unsigned*)(lds + (bufoff) + ldsw + _i * 8192), 16, 0, 0); } while (0)
; #define PG8_LDA(dst, b, h) do { _Pragma("unroll") for (int m = 0; m < 4; ++m) _Pragma("unroll") for (int k = 0; k < 2; ++k) dst[m][k] = *(const PG8_LAS bf16x8*)(lds + PG8_SA(b, h) + aoff + m * 2048 + k * 1024); } while (0)
; #define PG8_MMA(ai, bj, At, Bt) do { __builtin_amdgcn_s_setprio(1); _Pragma("unroll") for (int m = 0; m < 4; ++m) _Pragma("unroll") for (int n = 0; n < 2; ++n) _Pragma("unroll") for (int k = 0; k < 2; ++k) \
;         acc[ai][bj][m][n] = __builtin_amdgcn_mfma_f32_16x16x32_bf16(Bt[n][k], At[m][k], acc[ai][bj][m][n], 0, 0, 0); __builtin_amdgcn_s_setprio(0); } while (0)
; #define PG8_WAIT_V(n) asm volatile("s_waitcnt vmcnt(" #n ")" ::: "memory")
; #define PG8_WAIT_L(n) asm volatile("s_waitcnt lgkmcnt(" #n ")" ::: "memory")
; #define PG8_BAR __builtin_amdgcn_s_barrier()
; #define PG8_SCHED __builtin_amdgcn_sched_barrier(0)
; template <class Epi, class Sched, bool ALIGN_EPI = false, bool SP2 = false>
; __device__ __forceinline__ void gemm_phase(PG8_LAS unsigned char* lds, const Gemm g, const Sched& S, const Epi& E) {
;     ...
;         for (int t = 0; t < nt; t += 2) {
;             const bool last = (t == nt - 2);
;             const char* a1 = cA + (size_t)(t + 1) * kstep;
;             const char* a2 = last ? nA : cA + (size_t)(t + 2) * kstep; const char* b2 = last ? nB : cB + (size_t)(t + 2) * kstep;
;     ...
;             PG8_LDA(At, 1, 1); PG8_STAGE(PG8_SB(1, 0), b3, voffB); PG8_STAGE(PG8_SB(1, 1), b3 + hstep, voffB); PG8_STAGE(PG8_SA(1, 0), a3, voffA);
;             PG8_WAIT_V(8); PG8_WAIT_L(0); PG8_BAR; PG8_MMA(1, 0, At, B0); PG8_MMA(1, 1, At, B1); PG8_BAR; PG8_SCHED;
	s_add_i32 s74, s92, s61
	v_lshl_add_u64 v[184:185], v[184:185], 0, s[22:23]
	s_mov_b32 m0, s74
	ds_read_b128 v[196:199], v190 offset:49152
	ds_read_b128 v[200:203], v190 offset:50176
	ds_read_b128 v[204:207], v190 offset:51200
	ds_read_b128 v[208:211], v190 offset:52224
	ds_read_b128 v[212:215], v190 offset:53248
	ds_read_b128 v[216:219], v190 offset:54272
	ds_read_b128 v[220:223], v190 offset:55296
	ds_read_b128 v[224:227], v190 offset:56320
	global_load_lds_dwordx4 v[184:185], off
	s_add_i32 m0, s74, 0x2000
	s_add_u32 s72, s72, 0x100080
	v_lshl_add_u64 v[184:185], v[228:229], 0, s[22:23]
	s_addc_u32 s73, s73, 0
	s_add_i32 s74, s93, s61
	global_load_lds_dwordx4 v[184:185], off
	v_lshl_add_u64 v[184:185], s[72:73], 0, v[146:147]
	s_mov_b32 m0, s74
	s_nop 0
	global_load_lds_dwordx4 v[184:185], off
	v_lshl_add_u64 v[184:185], s[72:73], 0, v[150:151]
	s_add_i32 m0, s74, 0x2000
	s_nop 0
	global_load_lds_dwordx4 v[184:185], off
	v_lshl_add_u64 v[184:185], v[230:231], 0, s[22:23]
	s_mov_b32 m0, s83
	s_nop 0
	global_load_lds_dwordx4 v[184:185], off
	v_lshl_add_u64 v[184:185], v[232:233], 0, s[22:23]
	s_mov_b32 m0, s84
	s_nop 0
	global_load_lds_dwordx4 v[184:185], off
	s_waitcnt vmcnt(8)
	s_waitcnt lgkmcnt(0)
	s_barrier
	s_setprio 1
	s_waitcnt lgkmcnt(0)
	v_mfma_f32_16x16x32_bf16 v[60:63], v[128:131], v[196:199], v[60:63]
	v_mfma_f32_16x16x32_bf16 v[56:59], v[136:139], v[196:199], v[56:59]
	v_mfma_f32_16x16x32_bf16 v[44:47], v[128:131], v[204:207], v[44:47]
	v_mfma_f32_16x16x32_bf16 v[40:43], v[136:139], v[204:207], v[40:43]
	v_mfma_f32_16x16x32_bf16 v[28:31], v[128:131], v[212:215], v[28:31]
	v_mfma_f32_16x16x32_bf16 v[24:27], v[136:139], v[212:215], v[24:27]
	v_mfma_f32_16x16x32_bf16 v[12:15], v[128:131], v[220:223], v[12:15]
	v_mfma_f32_16x16x32_bf16 v[8:11], v[136:139], v[220:223], v[8:11]
	v_mfma_f32_16x16x32_bf16 v[60:63], v[132:135], v[200:203], v[60:63]
	v_mfma_f32_16x16x32_bf16 v[56:59], v[140:143], v[200:203], v[56:59]
	v_mfma_f32_16x16x32_bf16 v[44:47], v[132:135], v[208:211], v[44:47]
	v_mfma_f32_16x16x32_bf16 v[40:43], v[140:143], v[208:211], v[40:43]
	v_mfma_f32_16x16x32_bf16 v[28:31], v[132:135], v[216:219], v[28:31]
	v_mfma_f32_16x16x32_bf16 v[24:27], v[140:143], v[216:219], v[24:27]
	v_mfma_f32_16x16x32_bf16 v[12:15], v[132:135], v[224:227], v[12:15]
	v_mfma_f32_16x16x32_bf16 v[8:11], v[140:143], v[224:227], v[8:11]
	v_mfma_f32_16x16x32_bf16 v[52:55], v[168:171], v[196:199], v[52:55]
	v_mfma_f32_16x16x32_bf16 v[48:51], v[176:179], v[196:199], v[48:51]
	v_mfma_f32_16x16x32_bf16 v[36:39], v[168:171], v[204:207], v[36:39]
	v_mfma_f32_16x16x32_bf16 v[32:35], v[176:179], v[204:207], v[32:35]
	v_mfma_f32_16x16x32_bf16 v[20:23], v[168:171], v[212:215], v[20:23]
	v_mfma_f32_16x16x32_bf16 v[16:19], v[176:179], v[212:215], v[16:19]
	v_mfma_f32_16x16x32_bf16 v[4:7], v[168:171], v[220:223], v[4:7]
	v_mfma_f32_16x16x32_bf16 v[0:3], v[176:179], v[220:223], v[0:3]
	v_mfma_f32_16x16x32_bf16 v[52:55], v[172:175], v[200:203], v[52:55]
	v_mfma_f32_16x16x32_bf16 v[48:51], v[180:183], v[200:203], v[48:51]
	v_mfma_f32_16x16x32_bf16 v[36:39], v[172:175], v[208:211], v[36:39]
	v_mfma_f32_16x16x32_bf16 v[32:35], v[180:183], v[208:211], v[32:35]
	v_mfma_f32_16x16x32_bf16 v[20:23], v[172:175], v[216:219], v[20:23]
	v_mfma_f32_16x16x32_bf16 v[16:19], v[180:183], v[216:219], v[16:19]
	v_mfma_f32_16x16x32_bf16 v[4:7], v[172:175], v[224:227], v[4:7]
	v_mfma_f32_16x16x32_bf16 v[0:3], v[180:183], v[224:227], v[0:3]
	s_setprio 0
	s_barrier
	s_add_i32 s91, s91, 2
	s_add_u32 s8, s8, 0x100
	s_addc_u32 s9, s9, 0
	s_add_u32 s67, s67, 0x100
	s_addc_u32 s90, s90, 0
	s_cmp_gt_u32 s91, 61
	s_cbranch_scc0 .LBB0_86
	s_and_b64 vcc, exec, s[24:25]
	s_cbranch_vccz .LBB0_89
	s_barrier

; #define PG8_STAGE(bufoff, gbase, voff) do { _Pragma("unroll") for (int _i = 0; _i < 2; ++_i) \
;         __builtin_amdgcn_global_load_lds((const unsigned*)((const char*)(gbase) + (voff)[_i]), (PG8_LAS unsigned*)(lds + (bufoff) + ldsw + _i * 8192), 16, 0, 0); } while (0)
; #define PG8_LDA(dst, b, h) do { _Pragma("unroll") for (int m = 0; m < 4; ++m) _Pragma("unroll") for (int k = 0; k < 2; ++k) dst[m][k] = *(const PG8_LAS bf16x8*)(lds + PG8_SA(b, h) + aoff + m * 2048 + k * 1024); } while (0)
; #define PG8_LDB(dst, b, h) do { _Pragma("unroll") for (int n = 0; n < 2; ++n) _Pragma("unroll") for (int k = 0; k < 2; ++k) dst[n][k] = *(const PG8_LAS bf16x8*)(lds + PG8_SB(b, h) + boff + n * 2048 + k * 1024); } while (0)
; #define PG8_MMA(ai, bj, At, Bt) do { __builtin_amdgcn_s_setprio(1); _Pragma("unroll") for (int m = 0; m < 4; ++m) _Pragma("unroll") for (int n = 0; n < 2; ++n) _Pragma("unroll") for (int k = 0; k < 2; ++k) \
;         acc[ai][bj][m][n] = __builtin_amdgcn_mfma_f32_16x16x32_bf16(Bt[n][k], At[m][k], acc[ai][bj][m][n], 0, 0, 0); __builtin_amdgcn_s_setprio(0); } while (0)
; #define PG8_WAIT_V(n) asm volatile("s_waitcnt vmcnt(" #n ")" ::: "memory")
; #define PG8_WAIT_L(n) asm volatile("s_waitcnt lgkmcnt(" #n ")" ::: "memory")
; #define PG8_BAR __builtin_amdgcn_s_barrier()
; #define PG8_SCHED __builtin_amdgcn_sched_barrier(0)
; template <class Epi, class Sched, bool ALIGN_EPI = false, bool SP2 = false>
; __device__ __forceinline__ void gemm_phase(PG8_LAS unsigned char* lds, const Gemm g, const Sched& S, const Epi& E) {
;     ...
;             PG8_LDB(B0, 0, 0); PG8_LDB(B1, 0, 1); PG8_SCHED; PG8_LDA(At, 0, 0); PG8_STAGE(PG8_SA(1, 1), a1 + hstep, voffA);
;             PG8_WAIT_V(8); PG8_WAIT_L(0); PG8_BAR; PG8_MMA(0, 0, At, B0); PG8_MMA(0, 1, At, B1); PG8_BAR; PG8_SCHED;
;             PG8_LDA(At, 0, 1); PG8_STAGE(PG8_SB(0, 0), b2, voffB); PG8_STAGE(PG8_SB(0, 1), b2 + hstep, voffB); PG8_STAGE(PG8_SA(0, 0), a2, voffA);
;             PG8_WAIT_V(8); PG8_WAIT_L(0); PG8_BAR; PG8_MMA(1, 0, At, B0); PG8_MMA(1, 1, At, B1); PG8_BAR; PG8_SCHED;
.LBB0_613:
	ds_read_b128 v[76:79], v221
	ds_read_b128 v[80:83], v221 offset:1024
	ds_read_b128 v[88:91], v221 offset:2048
	ds_read_b128 v[96:99], v221 offset:3072
	ds_read_b128 v[144:147], v222
	ds_read_b128 v[148:151], v222 offset:1024
	ds_read_b128 v[152:155], v222 offset:2048
	ds_read_b128 v[156:159], v222 offset:3072
	s_add_u32 s46, s44, 0xfff00080
	s_addc_u32 s47, s45, -1
	s_cmp_eq_u32 s72, 60
	s_cselect_b32 s49, s27, s47
	s_cselect_b32 s48, s41, s46
	s_cselect_b32 s47, s25, s71
	s_cselect_b32 s46, s69, s70
	v_lshl_add_u64 v[206:207], s[44:45], 0, v[198:199]
	s_add_i32 m0, s43, 0xc000
	ds_read_b128 v[160:163], v223
	ds_read_b128 v[164:167], v223 offset:1024
	ds_read_b128 v[168:171], v223 offset:2048
	ds_read_b128 v[172:175], v223 offset:3072
	ds_read_b128 v[176:179], v223 offset:4096
	ds_read_b128 v[180:183], v223 offset:5120
	ds_read_b128 v[184:187], v223 offset:6144
	ds_read_b128 v[188:191], v223 offset:7168
	global_load_lds_dwordx4 v[206:207], off
	v_lshl_add_u64 v[206:207], s[44:45], 0, v[200:201]
	s_add_i32 m0, s43, 0xe000
	s_nop 0
	global_load_lds_dwordx4 v[206:207], off
	s_waitcnt vmcnt(8)
	s_waitcnt lgkmcnt(0)
	s_barrier
	s_setprio 1
	s_waitcnt lgkmcnt(0)
	v_mfma_f32_16x16x32_bf16 v[140:143], v[76:79], v[160:163], v[140:143]
	v_mfma_f32_16x16x32_bf16 v[136:139], v[88:91], v[160:163], v[136:139]
	v_mfma_f32_16x16x32_bf16 v[124:127], v[76:79], v[168:171], v[124:127]
	v_mfma_f32_16x16x32_bf16 v[120:123], v[88:91], v[168:171], v[120:123]
	v_mfma_f32_16x16x32_bf16 v[108:111], v[76:79], v[176:179], v[108:111]
	v_mfma_f32_16x16x32_bf16 v[104:107], v[88:91], v[176:179], v[104:107]
	v_mfma_f32_16x16x32_bf16 v[84:87], v[76:79], v[184:187], v[84:87]
	v_mfma_f32_16x16x32_bf16 v[72:75], v[88:91], v[184:187], v[72:75]
	v_mfma_f32_16x16x32_bf16 v[140:143], v[80:83], v[164:167], v[140:143]
	v_mfma_f32_16x16x32_bf16 v[136:139], v[96:99], v[164:167], v[136:139]
	v_mfma_f32_16x16x32_bf16 v[124:127], v[80:83], v[172:175], v[124:127]
	v_mfma_f32_16x16x32_bf16 v[120:123], v[96:99], v[172:175], v[120:123]
	v_mfma_f32_16x16x32_bf16 v[108:111], v[80:83], v[180:183], v[108:111]
	v_mfma_f32_16x16x32_bf16 v[104:107], v[96:99], v[180:183], v[104:107]
	v_mfma_f32_16x16x32_bf16 v[84:87], v[80:83], v[188:191], v[84:87]
	v_mfma_f32_16x16x32_bf16 v[72:75], v[96:99], v[188:191], v[72:75]
	v_mfma_f32_16x16x32_bf16 v[132:135], v[144:147], v[160:163], v[132:135]
	v_mfma_f32_16x16x32_bf16 v[128:131], v[152:155], v[160:163], v[128:131]
	v_mfma_f32_16x16x32_bf16 v[116:119], v[144:147], v[168:171], v[116:119]
	v_mfma_f32_16x16x32_bf16 v[112:115], v[152:155], v[168:171], v[112:115]
	v_mfma_f32_16x16x32_bf16 v[100:103], v[144:147], v[176:179], v[100:103]
	v_mfma_f32_16x16x32_bf16 v[92:95], v[152:155], v[176:179], v[92:95]
	v_mfma_f32_16x16x32_bf16 v[68:71], v[144:147], v[184:187], v[68:71]
	v_mfma_f32_16x16x32_bf16 v[64:67], v[152:155], v[184:187], v[64:67]
	v_mfma_f32_16x16x32_bf16 v[132:135], v[148:151], v[164:167], v[132:135]
	v_mfma_f32_16x16x32_bf16 v[128:131], v[156:159], v[164:167], v[128:131]
	v_mfma_f32_16x16x32_bf16 v[116:119], v[148:151], v[172:175], v[116:119]
	v_mfma_f32_16x16x32_bf16 v[112:115], v[156:159], v[172:175], v[112:115]
	v_mfma_f32_16x16x32_bf16 v[100:103], v[148:151], v[180:183], v[100:103]
	v_mfma_f32_16x16x32_bf16 v[92:95], v[156:159], v[180:183], v[92:95]
	v_mfma_f32_16x16x32_bf16 v[68:71], v[148:151], v[188:191], v[68:71]
	v_mfma_f32_16x16x32_bf16 v[64:67], v[156:159], v[188:191], v[64:67]
	s_setprio 0
	s_barrier
	s_add_i32 s73, s67, s54
	v_lshl_add_u64 v[206:207], s[46:47], 0, v[194:195]
	s_mov_b32 m0, s73
	ds_read_b128 v[160:163], v223 offset:16384
	ds_read_b128 v[164:167], v223 offset:17408
	ds_read_b128 v[168:171], v223 offset:18432
	ds_read_b128 v[172:175], v223 offset:19456
	ds_read_b128 v[176:179], v223 offset:20480
	ds_read_b128 v[180:183], v223 offset:21504
	ds_read_b128 v[184:187], v223 offset:22528
	ds_read_b128 v[188:191], v223 offset:23552
	global_load_lds_dwordx4 v[206:207], off
	s_add_i32 m0, s73, 0x2000
	s_add_u32 s74, s46, 0x100000
	v_lshl_add_u64 v[208:209], s[46:47], 0, v[196:197]
	s_addc_u32 s75, s47, 0
	s_add_i32 s73, s68, s54
	global_load_lds_dwordx4 v[208:209], off
	v_lshl_add_u64 v[210:211], s[74:75], 0, v[194:195]
	s_mov_b32 m0, s73
	v_lshl_add_u64 v[212:213], s[48:49], 0, v[196:197]
	global_load_lds_dwordx4 v[210:211], off
	v_lshl_add_u64 v[210:211], s[74:75], 0, v[196:197]
	s_add_i32 m0, s73, 0x2000
	s_nop 0
	global_load_lds_dwordx4 v[210:211], off
	v_lshl_add_u64 v[210:211], s[48:49], 0, v[194:195]
	s_mov_b32 m0, s43
	s_nop 0
	global_load_lds_dwordx4 v[210:211], off
	s_mov_b32 m0, s56
	s_nop 0
	global_load_lds_dwordx4 v[212:213], off
	s_waitcnt vmcnt(8)
	s_waitcnt lgkmcnt(0)
	s_barrier
; #define PG8_STAGE(bufoff, gbase, voff) do { _Pragma("unroll") for (int _i = 0; _i < 2; ++_i) \
;         __builtin_amdgcn_global_load_lds((const unsigned*)((const char*)(gbase) + (voff)[_i]), (PG8_LAS unsigned*)(lds + (bufoff) + ldsw + _i * 8192), 16, 0, 0); } while (0)
; #define PG8_LDA(dst, b, h) do { _Pragma("unroll") for (int m = 0; m < 4; ++m) _Pragma("unroll") for (int k = 0; k < 2; ++k) dst[m][k] = *(const PG8_LAS bf16x8*)(lds + PG8_SA(b, h) + aoff + m * 2048 + k * 1024); } while (0)
; #define PG8_LDB(dst, b, h) do { _Pragma("unroll") for (int n = 0; n < 2; ++n) _Pragma("unroll") for (int k = 0; k < 2; ++k) dst[n][k] = *(const PG8_LAS bf16x8*)(lds + PG8_SB(b, h) + boff + n * 2048 + k * 1024); } while (0)
; #define PG8_MMA(ai, bj, At, Bt) do { __builtin_amdgcn_s_setprio(1); _Pragma("unroll") for (int m = 0; m < 4; ++m) _Pragma("unroll") for (int n = 0; n < 2; ++n) _Pragma("unroll") for (int k = 0; k < 2; ++k) \
;         acc[ai][bj][m][n] = __builtin_amdgcn_mfma_f32_16x16x32_bf16(Bt[n][k], At[m][k], acc[ai][bj][m][n], 0, 0, 0); __builtin_amdgcn_s_setprio(0); } while (0)
; #define PG8_WAIT_V(n) asm volatile("s_waitcnt vmcnt(" #n ")" ::: "memory")
; #define PG8_WAIT_L(n) asm volatile("s_waitcnt lgkmcnt(" #n ")" ::: "memory")
; #define PG8_BAR __builtin_amdgcn_s_barrier()
; #define PG8_SCHED __builtin_amdgcn_sched_barrier(0)
; template <class Epi, class Sched, bool ALIGN_EPI = false, bool SP2 = false>
; __device__ __forceinline__ void gemm_phase(PG8_LAS unsigned char* lds, const Gemm g, const Sched& S, const Epi& E) {
;     ...
;             PG8_WAIT_V(8); PG8_WAIT_L(0); PG8_BAR; PG8_MMA(1, 0, At, B0); PG8_MMA(1, 1, At, B1); PG8_BAR; PG8_SCHED;
;             PG8_LDB(B0, 1, 0); PG8_LDB(B1, 1, 1); PG8_SCHED; PG8_LDA(At, 1, 0); PG8_STAGE(PG8_SA(0, 1), a2 + hstep, voffA);
;             PG8_WAIT_V(8); PG8_WAIT_L(0); PG8_BAR; PG8_MMA(0, 0, At, B0); PG8_MMA(0, 1, At, B1); PG8_BAR; PG8_SCHED;
	s_setprio 1
	s_waitcnt lgkmcnt(0)
	v_mfma_f32_16x16x32_bf16 v[60:63], v[76:79], v[160:163], v[60:63]
	v_mfma_f32_16x16x32_bf16 v[56:59], v[88:91], v[160:163], v[56:59]
	v_mfma_f32_16x16x32_bf16 v[44:47], v[76:79], v[168:171], v[44:47]
	v_mfma_f32_16x16x32_bf16 v[40:43], v[88:91], v[168:171], v[40:43]
	v_mfma_f32_16x16x32_bf16 v[28:31], v[76:79], v[176:179], v[28:31]
	v_mfma_f32_16x16x32_bf16 v[24:27], v[88:91], v[176:179], v[24:27]
	v_mfma_f32_16x16x32_bf16 v[12:15], v[76:79], v[184:187], v[12:15]
	v_mfma_f32_16x16x32_bf16 v[8:11], v[88:91], v[184:187], v[8:11]
	v_mfma_f32_16x16x32_bf16 v[60:63], v[80:83], v[164:167], v[60:63]
	v_mfma_f32_16x16x32_bf16 v[56:59], v[96:99], v[164:167], v[56:59]
	v_mfma_f32_16x16x32_bf16 v[44:47], v[80:83], v[172:175], v[44:47]
	v_mfma_f32_16x16x32_bf16 v[40:43], v[96:99], v[172:175], v[40:43]
	v_mfma_f32_16x16x32_bf16 v[28:31], v[80:83], v[180:183], v[28:31]
	v_mfma_f32_16x16x32_bf16 v[24:27], v[96:99], v[180:183], v[24:27]
	v_mfma_f32_16x16x32_bf16 v[12:15], v[80:83], v[188:191], v[12:15]
	v_mfma_f32_16x16x32_bf16 v[8:11], v[96:99], v[188:191], v[8:11]
	v_mfma_f32_16x16x32_bf16 v[52:55], v[144:147], v[160:163], v[52:55]
	v_mfma_f32_16x16x32_bf16 v[48:51], v[152:155], v[160:163], v[48:51]
	v_mfma_f32_16x16x32_bf16 v[36:39], v[144:147], v[168:171], v[36:39]
	v_mfma_f32_16x16x32_bf16 v[32:35], v[152:155], v[168:171], v[32:35]
	v_mfma_f32_16x16x32_bf16 v[20:23], v[144:147], v[176:179], v[20:23]
	v_mfma_f32_16x16x32_bf16 v[16:19], v[152:155], v[176:179], v[16:19]
	v_mfma_f32_16x16x32_bf16 v[4:7], v[144:147], v[184:187], v[4:7]
	v_mfma_f32_16x16x32_bf16 v[0:3], v[152:155], v[184:187], v[0:3]
	v_mfma_f32_16x16x32_bf16 v[52:55], v[148:151], v[164:167], v[52:55]
	v_mfma_f32_16x16x32_bf16 v[48:51], v[156:159], v[164:167], v[48:51]
	v_mfma_f32_16x16x32_bf16 v[36:39], v[148:151], v[172:175], v[36:39]
	v_mfma_f32_16x16x32_bf16 v[32:35], v[156:159], v[172:175], v[32:35]
	v_mfma_f32_16x16x32_bf16 v[20:23], v[148:151], v[180:183], v[20:23]
	v_mfma_f32_16x16x32_bf16 v[16:19], v[156:159], v[180:183], v[16:19]
	v_mfma_f32_16x16x32_bf16 v[4:7], v[148:151], v[188:191], v[4:7]
	v_mfma_f32_16x16x32_bf16 v[0:3], v[156:159], v[188:191], v[0:3]
	s_setprio 0
	s_barrier
	s_add_i32 s73, 0, 0x18000
	s_add_i32 s74, 0, 0x1c000
	v_add_u32_e32 v96, s73, v219
	v_add_u32_e32 v156, s74, v219
	ds_read_b128 v[76:79], v96
	ds_read_b128 v[80:83], v96 offset:1024
	ds_read_b128 v[88:91], v96 offset:2048
	ds_read_b128 v[96:99], v96 offset:3072
	ds_read_b128 v[144:147], v156
	ds_read_b128 v[148:151], v156 offset:1024
	ds_read_b128 v[152:155], v156 offset:2048
	ds_read_b128 v[156:159], v156 offset:3072
	s_add_u32 s48, s48, 0x100000
	s_addc_u32 s49, s49, 0
	s_mov_b32 m0, s58
	v_lshl_add_u64 v[214:215], s[48:49], 0, v[194:195]
	ds_read_b128 v[160:163], v223 offset:32768
	ds_read_b128 v[164:167], v223 offset:33792
	ds_read_b128 v[168:171], v223 offset:34816
	ds_read_b128 v[172:175], v223 offset:35840
	ds_read_b128 v[176:179], v223 offset:36864
	ds_read_b128 v[180:183], v223 offset:37888
	ds_read_b128 v[184:187], v223 offset:38912
	ds_read_b128 v[188:191], v223 offset:39936
	global_load_lds_dwordx4 v[214:215], off
	v_lshl_add_u64 v[214:215], s[48:49], 0, v[196:197]
	s_mov_b32 m0, s60
	s_nop 0
	global_load_lds_dwordx4 v[214:215], off
	s_waitcnt vmcnt(8)
	s_waitcnt lgkmcnt(0)
	s_barrier
	s_setprio 1
	s_waitcnt lgkmcnt(0)
	v_mfma_f32_16x16x32_bf16 v[140:143], v[76:79], v[160:163], v[140:143]
	v_mfma_f32_16x16x32_bf16 v[136:139], v[88:91], v[160:163], v[136:139]
	v_mfma_f32_16x16x32_bf16 v[124:127], v[76:79], v[168:171], v[124:127]
	v_mfma_f32_16x16x32_bf16 v[120:123], v[88:91], v[168:171], v[120:123]
	v_mfma_f32_16x16x32_bf16 v[108:111], v[76:79], v[176:179], v[108:111]
	v_mfma_f32_16x16x32_bf16 v[104:107], v[88:91], v[176:179], v[104:107]
	v_mfma_f32_16x16x32_bf16 v[84:87], v[76:79], v[184:187], v[84:87]
	v_mfma_f32_16x16x32_bf16 v[72:75], v[88:91], v[184:187], v[72:75]
	v_mfma_f32_16x16x32_bf16 v[140:143], v[80:83], v[164:167], v[140:143]
	v_mfma_f32_16x16x32_bf16 v[136:139], v[96:99], v[164:167], v[136:139]
	v_mfma_f32_16x16x32_bf16 v[124:127], v[80:83], v[172:175], v[124:127]
	v_mfma_f32_16x16x32_bf16 v[120:123], v[96:99], v[172:175], v[120:123]
	v_mfma_f32_16x16x32_bf16 v[108:111], v[80:83], v[180:183], v[108:111]
	v_mfma_f32_16x16x32_bf16 v[104:107], v[96:99], v[180:183], v[104:107]
	v_mfma_f32_16x16x32_bf16 v[84:87], v[80:83], v[188:191], v[84:87]
	v_mfma_f32_16x16x32_bf16 v[72:75], v[96:99], v[188:191], v[72:75]
	v_mfma_f32_16x16x32_bf16 v[132:135], v[144:147], v[160:163], v[132:135]
	v_mfma_f32_16x16x32_bf16 v[128:131], v[152:155], v[160:163], v[128:131]
	v_mfma_f32_16x16x32_bf16 v[116:119], v[144:147], v[168:171], v[116:119]
	v_mfma_f32_16x16x32_bf16 v[112:115], v[152:155], v[168:171], v[112:115]
	v_mfma_f32_16x16x32_bf16 v[100:103], v[144:147], v[176:179], v[100:103]
	v_mfma_f32_16x16x32_bf16 v[92:95], v[152:155], v[176:179], v[92:95]
	v_mfma_f32_16x16x32_bf16 v[68:71], v[144:147], v[184:187], v[68:71]
	v_mfma_f32_16x16x32_bf16 v[64:67], v[152:155], v[184:187], v[64:67]
	v_mfma_f32_16x16x32_bf16 v[132:135], v[148:151], v[164:167], v[132:135]
	v_mfma_f32_16x16x32_bf16 v[128:131], v[156:159], v[164:167], v[128:131]
	v_mfma_f32_16x16x32_bf16 v[116:119], v[148:151], v[172:175], v[116:119]
	v_mfma_f32_16x16x32_bf16 v[112:115], v[156:159], v[172:175], v[112:115]
	v_mfma_f32_16x16x32_bf16 v[100:103], v[148:151], v[180:183], v[100:103]
	v_mfma_f32_16x16x32_bf16 v[92:95], v[156:159], v[180:183], v[92:95]
	v_mfma_f32_16x16x32_bf16 v[68:71], v[148:151], v[188:191], v[68:71]
	v_mfma_f32_16x16x32_bf16 v[64:67], v[156:159], v[188:191], v[64:67]
	s_setprio 0
	s_barrier
; #define PG8_STAGE(bufoff, gbase, voff) do { _Pragma("unroll") for (int _i = 0; _i < 2; ++_i) \
;         __builtin_amdgcn_global_load_lds((const unsigned*)((const char*)(gbase) + (voff)[_i]), (PG8_LAS unsigned*)(lds + (bufoff) + ldsw + _i * 8192), 16, 0, 0); } while (0)
; #define PG8_LDA(dst, b, h) do { _Pragma("unroll") for (int m = 0; m < 4; ++m) _Pragma("unroll") for (int k = 0; k < 2; ++k) dst[m][k] = *(const PG8_LAS bf16x8*)(lds + PG8_SA(b, h) + aoff + m * 2048 + k * 1024); } while (0)
; #define PG8_MMA(ai, bj, At, Bt) do { __builtin_amdgcn_s_setprio(1); _Pragma("unroll") for (int m = 0; m < 4; ++m) _Pragma("unroll") for (int n = 0; n < 2; ++n) _Pragma("unroll") for (int k = 0; k < 2; ++k) \
;         acc[ai][bj][m][n] = __builtin_amdgcn_mfma_f32_16x16x32_bf16(Bt[n][k], At[m][k], acc[ai][bj][m][n], 0, 0, 0); __builtin_amdgcn_s_setprio(0); } while (0)
; #define PG8_WAIT_V(n) asm volatile("s_waitcnt vmcnt(" #n ")" ::: "memory")
; #define PG8_WAIT_L(n) asm volatile("s_waitcnt lgkmcnt(" #n ")" ::: "memory")
; #define PG8_BAR __builtin_amdgcn_s_barrier()
; #define PG8_SCHED __builtin_amdgcn_sched_barrier(0)
; template <class Epi, class Sched, bool ALIGN_EPI = false, bool SP2 = false>
; __device__ __forceinline__ void gemm_phase(PG8_LAS unsigned char* lds, const Gemm g, const Sched& S, const Epi& E) {
;     ...
;         for (int t = 0; t < nt; t += 2) {
;             const bool last = (t == nt - 2);
;             const char* a1 = cA + (size_t)(t + 1) * kstep;
;             const char* a2 = last ? nA : cA + (size_t)(t + 2) * kstep; const char* b2 = last ? nB : cB + (size_t)(t + 2) * kstep;
;     ...
;             PG8_LDA(At, 1, 1); PG8_STAGE(PG8_SB(1, 0), b3, voffB); PG8_STAGE(PG8_SB(1, 1), b3 + hstep, voffB); PG8_STAGE(PG8_SA(1, 0), a3, voffA);
;             PG8_WAIT_V(8); PG8_WAIT_L(0); PG8_BAR; PG8_MMA(1, 0, At, B0); PG8_MMA(1, 1, At, B1); PG8_BAR; PG8_SCHED;
	s_add_i32 s48, s73, s54
	v_lshl_add_u64 v[206:207], v[206:207], 0, s[20:21]
	s_mov_b32 m0, s48
	ds_read_b128 v[160:163], v223 offset:49152
	ds_read_b128 v[164:167], v223 offset:50176
	ds_read_b128 v[168:171], v223 offset:51200
	ds_read_b128 v[172:175], v223 offset:52224
	ds_read_b128 v[176:179], v223 offset:53248
	ds_read_b128 v[180:183], v223 offset:54272
	ds_read_b128 v[184:187], v223 offset:55296
	ds_read_b128 v[188:191], v223 offset:56320
	global_load_lds_dwordx4 v[206:207], off
	s_add_i32 m0, s48, 0x2000
	s_add_u32 s46, s46, 0x100080
	v_lshl_add_u64 v[206:207], v[208:209], 0, s[20:21]
	s_addc_u32 s47, s47, 0
	s_add_i32 s48, s74, s54
	global_load_lds_dwordx4 v[206:207], off
	v_lshl_add_u64 v[206:207], s[46:47], 0, v[194:195]
	s_mov_b32 m0, s48
	s_nop 0
	global_load_lds_dwordx4 v[206:207], off
	v_lshl_add_u64 v[206:207], s[46:47], 0, v[196:197]
	s_add_i32 m0, s48, 0x2000
	s_nop 0
	global_load_lds_dwordx4 v[206:207], off
	v_lshl_add_u64 v[206:207], v[210:211], 0, s[20:21]
	s_mov_b32 m0, s64
	s_nop 0
	global_load_lds_dwordx4 v[206:207], off
	v_lshl_add_u64 v[206:207], v[212:213], 0, s[20:21]
	s_mov_b32 m0, s65
	s_nop 0
	global_load_lds_dwordx4 v[206:207], off
	s_waitcnt vmcnt(8)
	s_waitcnt lgkmcnt(0)
	s_barrier
	s_setprio 1
	s_waitcnt lgkmcnt(0)
	v_mfma_f32_16x16x32_bf16 v[60:63], v[76:79], v[160:163], v[60:63]
	v_mfma_f32_16x16x32_bf16 v[56:59], v[88:91], v[160:163], v[56:59]
	v_mfma_f32_16x16x32_bf16 v[44:47], v[76:79], v[168:171], v[44:47]
	v_mfma_f32_16x16x32_bf16 v[40:43], v[88:91], v[168:171], v[40:43]
	v_mfma_f32_16x16x32_bf16 v[28:31], v[76:79], v[176:179], v[28:31]
	v_mfma_f32_16x16x32_bf16 v[24:27], v[88:91], v[176:179], v[24:27]
	v_mfma_f32_16x16x32_bf16 v[12:15], v[76:79], v[184:187], v[12:15]
	v_mfma_f32_16x16x32_bf16 v[8:11], v[88:91], v[184:187], v[8:11]
	v_mfma_f32_16x16x32_bf16 v[60:63], v[80:83], v[164:167], v[60:63]
	v_mfma_f32_16x16x32_bf16 v[56:59], v[96:99], v[164:167], v[56:59]
	v_mfma_f32_16x16x32_bf16 v[44:47], v[80:83], v[172:175], v[44:47]
	v_mfma_f32_16x16x32_bf16 v[40:43], v[96:99], v[172:175], v[40:43]
	v_mfma_f32_16x16x32_bf16 v[28:31], v[80:83], v[180:183], v[28:31]
	v_mfma_f32_16x16x32_bf16 v[24:27], v[96:99], v[180:183], v[24:27]
	v_mfma_f32_16x16x32_bf16 v[12:15], v[80:83], v[188:191], v[12:15]
	v_mfma_f32_16x16x32_bf16 v[8:11], v[96:99], v[188:191], v[8:11]
	v_mfma_f32_16x16x32_bf16 v[52:55], v[144:147], v[160:163], v[52:55]
	v_mfma_f32_16x16x32_bf16 v[48:51], v[152:155], v[160:163], v[48:51]
	v_mfma_f32_16x16x32_bf16 v[36:39], v[144:147], v[168:171], v[36:39]
	v_mfma_f32_16x16x32_bf16 v[32:35], v[152:155], v[168:171], v[32:35]
	v_mfma_f32_16x16x32_bf16 v[20:23], v[144:147], v[176:179], v[20:23]
	v_mfma_f32_16x16x32_bf16 v[16:19], v[152:155], v[176:179], v[16:19]
	v_mfma_f32_16x16x32_bf16 v[4:7], v[144:147], v[184:187], v[4:7]
	v_mfma_f32_16x16x32_bf16 v[0:3], v[152:155], v[184:187], v[0:3]
	v_mfma_f32_16x16x32_bf16 v[52:55], v[148:151], v[164:167], v[52:55]
	v_mfma_f32_16x16x32_bf16 v[48:51], v[156:159], v[164:167], v[48:51]
	v_mfma_f32_16x16x32_bf16 v[36:39], v[148:151], v[172:175], v[36:39]
	v_mfma_f32_16x16x32_bf16 v[32:35], v[156:159], v[172:175], v[32:35]
	v_mfma_f32_16x16x32_bf16 v[20:23], v[148:151], v[180:183], v[20:23]
	v_mfma_f32_16x16x32_bf16 v[16:19], v[156:159], v[180:183], v[16:19]
	v_mfma_f32_16x16x32_bf16 v[4:7], v[148:151], v[188:191], v[4:7]
	v_mfma_f32_16x16x32_bf16 v[0:3], v[156:159], v[188:191], v[0:3]
	s_setprio 0
	s_barrier
	s_add_i32 s72, s72, 2
	s_add_u32 s44, s44, 0x100
	s_addc_u32 s45, s45, 0
	s_add_u32 s70, s70, 0x100
	s_addc_u32 s71, s71, 0
	s_cmp_gt_u32 s72, 61
	s_cbranch_scc0 .LBB0_613
	s_and_b64 vcc, exec, s[22:23]
	s_cbranch_vccz .LBB0_616
	s_barrier

; #define PG8_STAGE(bufoff, gbase, voff) do { _Pragma("unroll") for (int _i = 0; _i < 2; ++_i) \
;         __builtin_amdgcn_global_load_lds((const unsigned*)((const char*)(gbase) + (voff)[_i]), (PG8_LAS unsigned*)(lds + (bufoff) + ldsw + _i * 8192), 16, 0, 0); } while (0)
; #define PG8_LDA(dst, b, h) do { _Pragma("unroll") for (int m = 0; m < 4; ++m) _Pragma("unroll") for (int k = 0; k < 2; ++k) dst[m][k] = *(const PG8_LAS bf16x8*)(lds + PG8_SA(b, h) + aoff + m * 2048 + k * 1024); } while (0)
; #define PG8_LDB(dst, b, h) do { _Pragma("unroll") for (int n = 0; n < 2; ++n) _Pragma("unroll") for (int k = 0; k < 2; ++k) dst[n][k] = *(const PG8_LAS bf16x8*)(lds + PG8_SB(b, h) + boff + n * 2048 + k * 1024); } while (0)
; #define PG8_MMA(ai, bj, At, Bt) do { __builtin_amdgcn_s_setprio(1); _Pragma("unroll") for (int m = 0; m < 4; ++m) _Pragma("unroll") for (int n = 0; n < 2; ++n) _Pragma("unroll") for (int k = 0; k < 2; ++k) \
;         acc[ai][bj][m][n] = __builtin_amdgcn_mfma_f32_16x16x32_bf16(Bt[n][k], At[m][k], acc[ai][bj][m][n], 0, 0, 0); __builtin_amdgcn_s_setprio(0); } while (0)
; #define PG8_WAIT_V(n) asm volatile("s_waitcnt vmcnt(" #n ")" ::: "memory")
; #define PG8_WAIT_L(n) asm volatile("s_waitcnt lgkmcnt(" #n ")" ::: "memory")
; #define PG8_BAR __builtin_amdgcn_s_barrier()
; #define PG8_SCHED __builtin_amdgcn_sched_barrier(0)
; template <class Epi, class Sched, bool ALIGN_EPI = false, bool SP2 = false>
; __device__ __forceinline__ void gemm_phase(PG8_LAS unsigned char* lds, const Gemm g, const Sched& S, const Epi& E) {
;     ...
;             PG8_LDB(B0, 0, 0); PG8_LDB(B1, 0, 1); PG8_SCHED; PG8_LDA(At, 0, 0); PG8_STAGE(PG8_SA(1, 1), a1 + hstep, voffA);
;             PG8_WAIT_V(8); PG8_WAIT_L(0); PG8_BAR; PG8_MMA(0, 0, At, B0); PG8_MMA(0, 1, At, B1); PG8_BAR; PG8_SCHED;
;             PG8_LDA(At, 0, 1); PG8_STAGE(PG8_SB(0, 0), b2, voffB); PG8_STAGE(PG8_SB(0, 1), b2 + hstep, voffB); PG8_STAGE(PG8_SA(0, 0), a2, voffA);
;             PG8_WAIT_V(8); PG8_WAIT_L(0); PG8_BAR; PG8_MMA(1, 0, At, B0); PG8_MMA(1, 1, At, B1); PG8_BAR; PG8_SCHED;
.LBB0_699:
	ds_read_b128 v[128:131], v208
	ds_read_b128 v[132:135], v208 offset:1024
	ds_read_b128 v[136:139], v208 offset:2048
	ds_read_b128 v[140:143], v208 offset:3072
	ds_read_b128 v[168:171], v209
	ds_read_b128 v[172:175], v209 offset:1024
	ds_read_b128 v[176:179], v209 offset:2048
	ds_read_b128 v[180:183], v209 offset:3072
	s_add_u32 s8, s6, 0xfff00080
	s_addc_u32 s9, s7, -1
	s_cmp_eq_u32 s94, 60
	s_cselect_b32 s13, s14, s9
	s_cselect_b32 s12, s15, s8
	s_cselect_b32 s9, s67, s93
	s_cselect_b32 s8, s69, s92
	v_lshl_add_u64 v[228:229], s[6:7], 0, v[160:161]
	s_add_i32 m0, s75, 0xc000
	ds_read_b128 v[184:187], v210
	ds_read_b128 v[188:191], v210 offset:1024
	ds_read_b128 v[194:197], v210 offset:2048
	ds_read_b128 v[198:201], v210 offset:3072
	ds_read_b128 v[202:205], v210 offset:4096
	ds_read_b128 v[216:219], v210 offset:5120
	ds_read_b128 v[220:223], v210 offset:6144
	ds_read_b128 v[224:227], v210 offset:7168
	global_load_lds_dwordx4 v[228:229], off
	v_lshl_add_u64 v[228:229], s[6:7], 0, v[162:163]
	s_add_i32 m0, s75, 0xe000
	s_nop 0
	global_load_lds_dwordx4 v[228:229], off
	s_waitcnt vmcnt(8)
	s_waitcnt lgkmcnt(0)
	s_barrier
	s_setprio 1
	s_waitcnt lgkmcnt(0)
	v_mfma_f32_16x16x32_bf16 v[124:127], v[128:131], v[184:187], v[124:127]
	v_mfma_f32_16x16x32_bf16 v[120:123], v[136:139], v[184:187], v[120:123]
	v_mfma_f32_16x16x32_bf16 v[108:111], v[128:131], v[194:197], v[108:111]
	v_mfma_f32_16x16x32_bf16 v[104:107], v[136:139], v[194:197], v[104:107]
	v_mfma_f32_16x16x32_bf16 v[92:95], v[128:131], v[202:205], v[92:95]
	v_mfma_f32_16x16x32_bf16 v[88:91], v[136:139], v[202:205], v[88:91]
	v_mfma_f32_16x16x32_bf16 v[76:79], v[128:131], v[220:223], v[76:79]
	v_mfma_f32_16x16x32_bf16 v[72:75], v[136:139], v[220:223], v[72:75]
	v_mfma_f32_16x16x32_bf16 v[124:127], v[132:135], v[188:191], v[124:127]
	v_mfma_f32_16x16x32_bf16 v[120:123], v[140:143], v[188:191], v[120:123]
	v_mfma_f32_16x16x32_bf16 v[108:111], v[132:135], v[198:201], v[108:111]
	v_mfma_f32_16x16x32_bf16 v[104:107], v[140:143], v[198:201], v[104:107]
	v_mfma_f32_16x16x32_bf16 v[92:95], v[132:135], v[216:219], v[92:95]
	v_mfma_f32_16x16x32_bf16 v[88:91], v[140:143], v[216:219], v[88:91]
	v_mfma_f32_16x16x32_bf16 v[76:79], v[132:135], v[224:227], v[76:79]
	v_mfma_f32_16x16x32_bf16 v[72:75], v[140:143], v[224:227], v[72:75]
	v_mfma_f32_16x16x32_bf16 v[116:119], v[168:171], v[184:187], v[116:119]
	v_mfma_f32_16x16x32_bf16 v[112:115], v[176:179], v[184:187], v[112:115]
	v_mfma_f32_16x16x32_bf16 v[100:103], v[168:171], v[194:197], v[100:103]
	v_mfma_f32_16x16x32_bf16 v[96:99], v[176:179], v[194:197], v[96:99]
	v_mfma_f32_16x16x32_bf16 v[84:87], v[168:171], v[202:205], v[84:87]
	v_mfma_f32_16x16x32_bf16 v[80:83], v[176:179], v[202:205], v[80:83]
	v_mfma_f32_16x16x32_bf16 v[68:71], v[168:171], v[220:223], v[68:71]
	v_mfma_f32_16x16x32_bf16 v[64:67], v[176:179], v[220:223], v[64:67]
	v_mfma_f32_16x16x32_bf16 v[116:119], v[172:175], v[188:191], v[116:119]
	v_mfma_f32_16x16x32_bf16 v[112:115], v[180:183], v[188:191], v[112:115]
	v_mfma_f32_16x16x32_bf16 v[100:103], v[172:175], v[198:201], v[100:103]
	v_mfma_f32_16x16x32_bf16 v[96:99], v[180:183], v[198:201], v[96:99]
	v_mfma_f32_16x16x32_bf16 v[84:87], v[172:175], v[216:219], v[84:87]
	v_mfma_f32_16x16x32_bf16 v[80:83], v[180:183], v[216:219], v[80:83]
	v_mfma_f32_16x16x32_bf16 v[68:71], v[172:175], v[224:227], v[68:71]
	v_mfma_f32_16x16x32_bf16 v[64:67], v[180:183], v[224:227], v[64:67]
	s_setprio 0
	s_barrier
	s_add_i32 s95, s88, s76
	v_lshl_add_u64 v[228:229], s[8:9], 0, v[146:147]
	s_mov_b32 m0, s95
	ds_read_b128 v[184:187], v210 offset:16384
	ds_read_b128 v[188:191], v210 offset:17408
	ds_read_b128 v[194:197], v210 offset:18432
	ds_read_b128 v[198:201], v210 offset:19456
	ds_read_b128 v[202:205], v210 offset:20480
	ds_read_b128 v[216:219], v210 offset:21504
	ds_read_b128 v[220:223], v210 offset:22528
	ds_read_b128 v[224:227], v210 offset:23552
	global_load_lds_dwordx4 v[228:229], off
	s_add_i32 m0, s95, 0x2000
	s_add_u32 s96, s8, 0x100000
	v_lshl_add_u64 v[230:231], s[8:9], 0, v[150:151]
	s_addc_u32 s97, s9, 0
	s_add_i32 s95, s89, s76
	global_load_lds_dwordx4 v[230:231], off
	v_lshl_add_u64 v[232:233], s[96:97], 0, v[146:147]
	s_mov_b32 m0, s95
	v_lshl_add_u64 v[234:235], s[12:13], 0, v[148:149]
	global_load_lds_dwordx4 v[232:233], off
	v_lshl_add_u64 v[232:233], s[96:97], 0, v[150:151]
	s_add_i32 m0, s95, 0x2000
	s_nop 0
	global_load_lds_dwordx4 v[232:233], off
	v_lshl_add_u64 v[232:233], s[12:13], 0, v[144:145]
	s_mov_b32 m0, s75
	s_nop 0
	global_load_lds_dwordx4 v[232:233], off
	s_mov_b32 m0, s77
	s_nop 0
	global_load_lds_dwordx4 v[234:235], off
	s_waitcnt vmcnt(8)
	s_waitcnt lgkmcnt(0)
	s_barrier
; #define PG8_STAGE(bufoff, gbase, voff) do { _Pragma("unroll") for (int _i = 0; _i < 2; ++_i) \
;         __builtin_amdgcn_global_load_lds((const unsigned*)((const char*)(gbase) + (voff)[_i]), (PG8_LAS unsigned*)(lds + (bufoff) + ldsw + _i * 8192), 16, 0, 0); } while (0)
; #define PG8_LDA(dst, b, h) do { _Pragma("unroll") for (int m = 0; m < 4; ++m) _Pragma("unroll") for (int k = 0; k < 2; ++k) dst[m][k] = *(const PG8_LAS bf16x8*)(lds + PG8_SA(b, h) + aoff + m * 2048 + k * 1024); } while (0)
; #define PG8_LDB(dst, b, h) do { _Pragma("unroll") for (int n = 0; n < 2; ++n) _Pragma("unroll") for (int k = 0; k < 2; ++k) dst[n][k] = *(const PG8_LAS bf16x8*)(lds + PG8_SB(b, h) + boff + n * 2048 + k * 1024); } while (0)
; #define PG8_MMA(ai, bj, At, Bt) do { __builtin_amdgcn_s_setprio(1); _Pragma("unroll") for (int m = 0; m < 4; ++m) _Pragma("unroll") for (int n = 0; n < 2; ++n) _Pragma("unroll") for (int k = 0; k < 2; ++k) \
;         acc[ai][bj][m][n] = __builtin_amdgcn_mfma_f32_16x16x32_bf16(Bt[n][k], At[m][k], acc[ai][bj][m][n], 0, 0, 0); __builtin_amdgcn_s_setprio(0); } while (0)
; #define PG8_WAIT_V(n) asm volatile("s_waitcnt vmcnt(" #n ")" ::: "memory")
; #define PG8_WAIT_L(n) asm volatile("s_waitcnt lgkmcnt(" #n ")" ::: "memory")
; #define PG8_BAR __builtin_amdgcn_s_barrier()
; #define PG8_SCHED __builtin_amdgcn_sched_barrier(0)
; template <class Epi, class Sched, bool ALIGN_EPI = false, bool SP2 = false>
; __device__ __forceinline__ void gemm_phase(PG8_LAS unsigned char* lds, const Gemm g, const Sched& S, const Epi& E) {
;     ...
;             PG8_WAIT_V(8); PG8_WAIT_L(0); PG8_BAR; PG8_MMA(1, 0, At, B0); PG8_MMA(1, 1, At, B1); PG8_BAR; PG8_SCHED;
;             PG8_LDB(B0, 1, 0); PG8_LDB(B1, 1, 1); PG8_SCHED; PG8_LDA(At, 1, 0); PG8_STAGE(PG8_SA(0, 1), a2 + hstep, voffA);
;             PG8_WAIT_V(8); PG8_WAIT_L(0); PG8_BAR; PG8_MMA(0, 0, At, B0); PG8_MMA(0, 1, At, B1); PG8_BAR; PG8_SCHED;
	s_setprio 1
	s_waitcnt lgkmcnt(0)
	v_mfma_f32_16x16x32_bf16 v[60:63], v[128:131], v[184:187], v[60:63]
	v_mfma_f32_16x16x32_bf16 v[56:59], v[136:139], v[184:187], v[56:59]
	v_mfma_f32_16x16x32_bf16 v[44:47], v[128:131], v[194:197], v[44:47]
	v_mfma_f32_16x16x32_bf16 v[40:43], v[136:139], v[194:197], v[40:43]
	v_mfma_f32_16x16x32_bf16 v[28:31], v[128:131], v[202:205], v[28:31]
	v_mfma_f32_16x16x32_bf16 v[24:27], v[136:139], v[202:205], v[24:27]
	v_mfma_f32_16x16x32_bf16 v[12:15], v[128:131], v[220:223], v[12:15]
	v_mfma_f32_16x16x32_bf16 v[8:11], v[136:139], v[220:223], v[8:11]
	v_mfma_f32_16x16x32_bf16 v[60:63], v[132:135], v[188:191], v[60:63]
	v_mfma_f32_16x16x32_bf16 v[56:59], v[140:143], v[188:191], v[56:59]
	v_mfma_f32_16x16x32_bf16 v[44:47], v[132:135], v[198:201], v[44:47]
	v_mfma_f32_16x16x32_bf16 v[40:43], v[140:143], v[198:201], v[40:43]
	v_mfma_f32_16x16x32_bf16 v[28:31], v[132:135], v[216:219], v[28:31]
	v_mfma_f32_16x16x32_bf16 v[24:27], v[140:143], v[216:219], v[24:27]
	v_mfma_f32_16x16x32_bf16 v[12:15], v[132:135], v[224:227], v[12:15]
	v_mfma_f32_16x16x32_bf16 v[8:11], v[140:143], v[224:227], v[8:11]
	v_mfma_f32_16x16x32_bf16 v[52:55], v[168:171], v[184:187], v[52:55]
	v_mfma_f32_16x16x32_bf16 v[48:51], v[176:179], v[184:187], v[48:51]
	v_mfma_f32_16x16x32_bf16 v[36:39], v[168:171], v[194:197], v[36:39]
	v_mfma_f32_16x16x32_bf16 v[32:35], v[176:179], v[194:197], v[32:35]
	v_mfma_f32_16x16x32_bf16 v[20:23], v[168:171], v[202:205], v[20:23]
	v_mfma_f32_16x16x32_bf16 v[16:19], v[176:179], v[202:205], v[16:19]
	v_mfma_f32_16x16x32_bf16 v[4:7], v[168:171], v[220:223], v[4:7]
	v_mfma_f32_16x16x32_bf16 v[0:3], v[176:179], v[220:223], v[0:3]
	v_mfma_f32_16x16x32_bf16 v[52:55], v[172:175], v[188:191], v[52:55]
	v_mfma_f32_16x16x32_bf16 v[48:51], v[180:183], v[188:191], v[48:51]
	v_mfma_f32_16x16x32_bf16 v[36:39], v[172:175], v[198:201], v[36:39]
	v_mfma_f32_16x16x32_bf16 v[32:35], v[180:183], v[198:201], v[32:35]
	v_mfma_f32_16x16x32_bf16 v[20:23], v[172:175], v[216:219], v[20:23]
	v_mfma_f32_16x16x32_bf16 v[16:19], v[180:183], v[216:219], v[16:19]
	v_mfma_f32_16x16x32_bf16 v[4:7], v[172:175], v[224:227], v[4:7]
	v_mfma_f32_16x16x32_bf16 v[0:3], v[180:183], v[224:227], v[0:3]
	s_setprio 0
	s_barrier
	s_add_i32 s95, 0, 0x18000
	s_add_i32 s96, 0, 0x1c000
	v_add_u32_e32 v140, s95, v207
	v_add_u32_e32 v152, s96, v207
	ds_read_b128 v[128:131], v140
	ds_read_b128 v[132:135], v140 offset:1024
	ds_read_b128 v[136:139], v140 offset:2048
	ds_read_b128 v[140:143], v140 offset:3072
	ds_read_b128 v[168:171], v152
	ds_read_b128 v[172:175], v152 offset:1024
	ds_read_b128 v[176:179], v152 offset:2048
	ds_read_b128 v[180:183], v152 offset:3072
	s_add_u32 s12, s12, 0x100000
	s_addc_u32 s13, s13, 0
	s_mov_b32 m0, s78
	v_lshl_add_u64 v[236:237], s[12:13], 0, v[144:145]
	ds_read_b128 v[184:187], v210 offset:32768
	ds_read_b128 v[188:191], v210 offset:33792
	ds_read_b128 v[194:197], v210 offset:34816
	ds_read_b128 v[198:201], v210 offset:35840
	ds_read_b128 v[202:205], v210 offset:36864
	ds_read_b128 v[216:219], v210 offset:37888
	ds_read_b128 v[220:223], v210 offset:38912
	ds_read_b128 v[224:227], v210 offset:39936
	global_load_lds_dwordx4 v[236:237], off
	v_lshl_add_u64 v[236:237], s[12:13], 0, v[148:149]
	s_mov_b32 m0, s79
	s_nop 0
	global_load_lds_dwordx4 v[236:237], off
	s_waitcnt vmcnt(8)
	s_waitcnt lgkmcnt(0)
	s_barrier
	s_setprio 1
	s_waitcnt lgkmcnt(0)
	v_mfma_f32_16x16x32_bf16 v[124:127], v[128:131], v[184:187], v[124:127]
	v_mfma_f32_16x16x32_bf16 v[120:123], v[136:139], v[184:187], v[120:123]
	v_mfma_f32_16x16x32_bf16 v[108:111], v[128:131], v[194:197], v[108:111]
	v_mfma_f32_16x16x32_bf16 v[104:107], v[136:139], v[194:197], v[104:107]
	v_mfma_f32_16x16x32_bf16 v[92:95], v[128:131], v[202:205], v[92:95]
	v_mfma_f32_16x16x32_bf16 v[88:91], v[136:139], v[202:205], v[88:91]
	v_mfma_f32_16x16x32_bf16 v[76:79], v[128:131], v[220:223], v[76:79]
	v_mfma_f32_16x16x32_bf16 v[72:75], v[136:139], v[220:223], v[72:75]
	v_mfma_f32_16x16x32_bf16 v[124:127], v[132:135], v[188:191], v[124:127]
	v_mfma_f32_16x16x32_bf16 v[120:123], v[140:143], v[188:191], v[120:123]
	v_mfma_f32_16x16x32_bf16 v[108:111], v[132:135], v[198:201], v[108:111]
	v_mfma_f32_16x16x32_bf16 v[104:107], v[140:143], v[198:201], v[104:107]
	v_mfma_f32_16x16x32_bf16 v[92:95], v[132:135], v[216:219], v[92:95]
	v_mfma_f32_16x16x32_bf16 v[88:91], v[140:143], v[216:219], v[88:91]
	v_mfma_f32_16x16x32_bf16 v[76:79], v[132:135], v[224:227], v[76:79]
	v_mfma_f32_16x16x32_bf16 v[72:75], v[140:143], v[224:227], v[72:75]
	v_mfma_f32_16x16x32_bf16 v[116:119], v[168:171], v[184:187], v[116:119]
	v_mfma_f32_16x16x32_bf16 v[112:115], v[176:179], v[184:187], v[112:115]
	v_mfma_f32_16x16x32_bf16 v[100:103], v[168:171], v[194:197], v[100:103]
	v_mfma_f32_16x16x32_bf16 v[96:99], v[176:179], v[194:197], v[96:99]
	v_mfma_f32_16x16x32_bf16 v[84:87], v[168:171], v[202:205], v[84:87]
	v_mfma_f32_16x16x32_bf16 v[80:83], v[176:179], v[202:205], v[80:83]
	v_mfma_f32_16x16x32_bf16 v[68:71], v[168:171], v[220:223], v[68:71]
	v_mfma_f32_16x16x32_bf16 v[64:67], v[176:179], v[220:223], v[64:67]
	v_mfma_f32_16x16x32_bf16 v[116:119], v[172:175], v[188:191], v[116:119]
	v_mfma_f32_16x16x32_bf16 v[112:115], v[180:183], v[188:191], v[112:115]
	v_mfma_f32_16x16x32_bf16 v[100:103], v[172:175], v[198:201], v[100:103]
	v_mfma_f32_16x16x32_bf16 v[96:99], v[180:183], v[198:201], v[96:99]
	v_mfma_f32_16x16x32_bf16 v[84:87], v[172:175], v[216:219], v[84:87]
	v_mfma_f32_16x16x32_bf16 v[80:83], v[180:183], v[216:219], v[80:83]
	v_mfma_f32_16x16x32_bf16 v[68:71], v[172:175], v[224:227], v[68:71]
	v_mfma_f32_16x16x32_bf16 v[64:67], v[180:183], v[224:227], v[64:67]
	s_setprio 0
	s_barrier
; #define PG8_STAGE(bufoff, gbase, voff) do { _Pragma("unroll") for (int _i = 0; _i < 2; ++_i) \
;         __builtin_amdgcn_global_load_lds((const unsigned*)((const char*)(gbase) + (voff)[_i]), (PG8_LAS unsigned*)(lds + (bufoff) + ldsw + _i * 8192), 16, 0, 0); } while (0)
; #define PG8_LDA(dst, b, h) do { _Pragma("unroll") for (int m = 0; m < 4; ++m) _Pragma("unroll") for (int k = 0; k < 2; ++k) dst[m][k] = *(const PG8_LAS bf16x8*)(lds + PG8_SA(b, h) + aoff + m * 2048 + k * 1024); } while (0)
; #define PG8_MMA(ai, bj, At, Bt) do { __builtin_amdgcn_s_setprio(1); _Pragma("unroll") for (int m = 0; m < 4; ++m) _Pragma("unroll") for (int n = 0; n < 2; ++n) _Pragma("unroll") for (int k = 0; k < 2; ++k) \
;         acc[ai][bj][m][n] = __builtin_amdgcn_mfma_f32_16x16x32_bf16(Bt[n][k], At[m][k], acc[ai][bj][m][n], 0, 0, 0); __builtin_amdgcn_s_setprio(0); } while (0)
; #define PG8_WAIT_V(n) asm volatile("s_waitcnt vmcnt(" #n ")" ::: "memory")
; #define PG8_WAIT_L(n) asm volatile("s_waitcnt lgkmcnt(" #n ")" ::: "memory")
; #define PG8_BAR __builtin_amdgcn_s_barrier()
; #define PG8_SCHED __builtin_amdgcn_sched_barrier(0)
; template <class Epi, class Sched, bool ALIGN_EPI = false, bool SP2 = false>
; __device__ __forceinline__ void gemm_phase(PG8_LAS unsigned char* lds, const Gemm g, const Sched& S, const Epi& E) {
;     ...
;         for (int t = 0; t < nt; t += 2) {
;             const bool last = (t == nt - 2);
;             const char* a1 = cA + (size_t)(t + 1) * kstep;
;             const char* a2 = last ? nA : cA + (size_t)(t + 2) * kstep; const char* b2 = last ? nB : cB + (size_t)(t + 2) * kstep;
;     ...
;             PG8_LDA(At, 1, 1); PG8_STAGE(PG8_SB(1, 0), b3, voffB); PG8_STAGE(PG8_SB(1, 1), b3 + hstep, voffB); PG8_STAGE(PG8_SA(1, 0), a3, voffA);
;             PG8_WAIT_V(8); PG8_WAIT_L(0); PG8_BAR; PG8_MMA(1, 0, At, B0); PG8_MMA(1, 1, At, B1); PG8_BAR; PG8_SCHED;
	s_add_i32 s12, s95, s76
	v_lshl_add_u64 v[228:229], v[228:229], 0, s[24:25]
	s_mov_b32 m0, s12
	ds_read_b128 v[184:187], v210 offset:49152
	ds_read_b128 v[188:191], v210 offset:50176
	ds_read_b128 v[194:197], v210 offset:51200
	ds_read_b128 v[198:201], v210 offset:52224
	ds_read_b128 v[202:205], v210 offset:53248
	ds_read_b128 v[216:219], v210 offset:54272
	ds_read_b128 v[220:223], v210 offset:55296
	ds_read_b128 v[224:227], v210 offset:56320
	global_load_lds_dwordx4 v[228:229], off
	s_add_i32 m0, s12, 0x2000
	s_add_u32 s8, s8, 0x100080
	v_lshl_add_u64 v[228:229], v[230:231], 0, s[24:25]
	s_addc_u32 s9, s9, 0
	s_add_i32 s12, s96, s76
	global_load_lds_dwordx4 v[228:229], off
	v_lshl_add_u64 v[228:229], s[8:9], 0, v[146:147]
	s_mov_b32 m0, s12
	s_nop 0
	global_load_lds_dwordx4 v[228:229], off
	v_lshl_add_u64 v[228:229], s[8:9], 0, v[150:151]
	s_add_i32 m0, s12, 0x2000
	s_nop 0
	global_load_lds_dwordx4 v[228:229], off
	v_lshl_add_u64 v[228:229], v[232:233], 0, s[24:25]
	s_mov_b32 m0, s85
	s_nop 0
	global_load_lds_dwordx4 v[228:229], off
	v_lshl_add_u64 v[228:229], v[234:235], 0, s[24:25]
	s_mov_b32 m0, s86
	s_nop 0
	global_load_lds_dwordx4 v[228:229], off
	s_waitcnt vmcnt(8)
	s_waitcnt lgkmcnt(0)
	s_barrier
	s_setprio 1
	s_waitcnt lgkmcnt(0)
	v_mfma_f32_16x16x32_bf16 v[60:63], v[128:131], v[184:187], v[60:63]
	v_mfma_f32_16x16x32_bf16 v[56:59], v[136:139], v[184:187], v[56:59]
	v_mfma_f32_16x16x32_bf16 v[44:47], v[128:131], v[194:197], v[44:47]
	v_mfma_f32_16x16x32_bf16 v[40:43], v[136:139], v[194:197], v[40:43]
	v_mfma_f32_16x16x32_bf16 v[28:31], v[128:131], v[202:205], v[28:31]
	v_mfma_f32_16x16x32_bf16 v[24:27], v[136:139], v[202:205], v[24:27]
	v_mfma_f32_16x16x32_bf16 v[12:15], v[128:131], v[220:223], v[12:15]
	v_mfma_f32_16x16x32_bf16 v[8:11], v[136:139], v[220:223], v[8:11]
	v_mfma_f32_16x16x32_bf16 v[60:63], v[132:135], v[188:191], v[60:63]
	v_mfma_f32_16x16x32_bf16 v[56:59], v[140:143], v[188:191], v[56:59]
	v_mfma_f32_16x16x32_bf16 v[44:47], v[132:135], v[198:201], v[44:47]
	v_mfma_f32_16x16x32_bf16 v[40:43], v[140:143], v[198:201], v[40:43]
	v_mfma_f32_16x16x32_bf16 v[28:31], v[132:135], v[216:219], v[28:31]
	v_mfma_f32_16x16x32_bf16 v[24:27], v[140:143], v[216:219], v[24:27]
	v_mfma_f32_16x16x32_bf16 v[12:15], v[132:135], v[224:227], v[12:15]
	v_mfma_f32_16x16x32_bf16 v[8:11], v[140:143], v[224:227], v[8:11]
	v_mfma_f32_16x16x32_bf16 v[52:55], v[168:171], v[184:187], v[52:55]
	v_mfma_f32_16x16x32_bf16 v[48:51], v[176:179], v[184:187], v[48:51]
	v_mfma_f32_16x16x32_bf16 v[36:39], v[168:171], v[194:197], v[36:39]
	v_mfma_f32_16x16x32_bf16 v[32:35], v[176:179], v[194:197], v[32:35]
	v_mfma_f32_16x16x32_bf16 v[20:23], v[168:171], v[202:205], v[20:23]
	v_mfma_f32_16x16x32_bf16 v[16:19], v[176:179], v[202:205], v[16:19]
	v_mfma_f32_16x16x32_bf16 v[4:7], v[168:171], v[220:223], v[4:7]
	v_mfma_f32_16x16x32_bf16 v[0:3], v[176:179], v[220:223], v[0:3]
	v_mfma_f32_16x16x32_bf16 v[52:55], v[172:175], v[188:191], v[52:55]
	v_mfma_f32_16x16x32_bf16 v[48:51], v[180:183], v[188:191], v[48:51]
	v_mfma_f32_16x16x32_bf16 v[36:39], v[172:175], v[198:201], v[36:39]
	v_mfma_f32_16x16x32_bf16 v[32:35], v[180:183], v[198:201], v[32:35]
	v_mfma_f32_16x16x32_bf16 v[20:23], v[172:175], v[216:219], v[20:23]
	v_mfma_f32_16x16x32_bf16 v[16:19], v[180:183], v[216:219], v[16:19]
	v_mfma_f32_16x16x32_bf16 v[4:7], v[172:175], v[224:227], v[4:7]
	v_mfma_f32_16x16x32_bf16 v[0:3], v[180:183], v[224:227], v[0:3]
	s_setprio 0
	s_barrier
	s_add_i32 s94, s94, 2
	s_add_u32 s6, s6, 0x100
	s_addc_u32 s7, s7, 0
	s_add_u32 s92, s92, 0x100
	s_addc_u32 s93, s93, 0
	s_cmp_gt_u32 s94, 61
	s_cbranch_scc0 .LBB0_699
	s_and_b64 vcc, exec, s[26:27]
	s_cbranch_vccz .LBB0_702
	s_barrier

; #define PG8_STAGE(bufoff, gbase, voff) do { _Pragma("unroll") for (int _i = 0; _i < 2; ++_i) \
;         __builtin_amdgcn_global_load_lds((const unsigned*)((const char*)(gbase) + (voff)[_i]), (PG8_LAS unsigned*)(lds + (bufoff) + ldsw + _i * 8192), 16, 0, 0); } while (0)
; #define PG8_LDA(dst, b, h) do { _Pragma("unroll") for (int m = 0; m < 4; ++m) _Pragma("unroll") for (int k = 0; k < 2; ++k) dst[m][k] = *(const PG8_LAS bf16x8*)(lds + PG8_SA(b, h) + aoff + m * 2048 + k * 1024); } while (0)
; #define PG8_LDB(dst, b, h) do { _Pragma("unroll") for (int n = 0; n < 2; ++n) _Pragma("unroll") for (int k = 0; k < 2; ++k) dst[n][k] = *(const PG8_LAS bf16x8*)(lds + PG8_SB(b, h) + boff + n * 2048 + k * 1024); } while (0)
; #define PG8_MMA(ai, bj, At, Bt) do { __builtin_amdgcn_s_setprio(1); _Pragma("unroll") for (int m = 0; m < 4; ++m) _Pragma("unroll") for (int n = 0; n < 2; ++n) _Pragma("unroll") for (int k = 0; k < 2; ++k) \
;         acc[ai][bj][m][n] = __builtin_amdgcn_mfma_f32_16x16x32_bf16(Bt[n][k], At[m][k], acc[ai][bj][m][n], 0, 0, 0); __builtin_amdgcn_s_setprio(0); } while (0)
; #define PG8_WAIT_V(n) asm volatile("s_waitcnt vmcnt(" #n ")" ::: "memory")
; #define PG8_WAIT_L(n) asm volatile("s_waitcnt lgkmcnt(" #n ")" ::: "memory")
; #define PG8_BAR __builtin_amdgcn_s_barrier()
; #define PG8_SCHED __builtin_amdgcn_sched_barrier(0)
; template <class Epi, class Sched, bool ALIGN_EPI = false, bool SP2 = false>
; __device__ __forceinline__ void gemm_phase(PG8_LAS unsigned char* lds, const Gemm g, const Sched& S, const Epi& E) {
;     ...
;             PG8_LDB(B0, 0, 0); PG8_LDB(B1, 0, 1); PG8_SCHED; PG8_LDA(At, 0, 0); PG8_STAGE(PG8_SA(1, 1), a1 + hstep, voffA);
;             PG8_WAIT_V(8); PG8_WAIT_L(0); PG8_BAR; PG8_MMA(0, 0, At, B0); PG8_MMA(0, 1, At, B1); PG8_BAR; PG8_SCHED;
;             PG8_LDA(At, 0, 1); PG8_STAGE(PG8_SB(0, 0), b2, voffB); PG8_STAGE(PG8_SB(0, 1), b2 + hstep, voffB); PG8_STAGE(PG8_SA(0, 0), a2, voffA);
;             PG8_WAIT_V(8); PG8_WAIT_L(0); PG8_BAR; PG8_MMA(1, 0, At, B0); PG8_MMA(1, 1, At, B1); PG8_BAR; PG8_SCHED;
.LBB0_1224:
	ds_read_b128 v[140:143], v149
	ds_read_b128 v[152:155], v149 offset:1024
	ds_read_b128 v[156:159], v149 offset:2048
	ds_read_b128 v[160:163], v149 offset:3072
	ds_read_b128 v[164:167], v150
	ds_read_b128 v[168:171], v150 offset:1024
	ds_read_b128 v[172:175], v150 offset:2048
	ds_read_b128 v[176:179], v150 offset:3072
	s_add_u32 s36, s26, 0xfff00080
	s_addc_u32 s37, s27, -1
	s_cmp_eq_u32 s64, 60
	s_cselect_b32 s39, s19, s37
	s_cselect_b32 s38, s60, s36
	s_cselect_b32 s37, s17, s63
	s_cselect_b32 s36, s61, s62
	v_lshl_add_u64 v[144:145], s[26:27], 0, v[132:133]
	s_add_i32 m0, s25, 0xc000
	ds_read_b128 v[180:183], v151
	ds_read_b128 v[184:187], v151 offset:1024
	ds_read_b128 v[188:191], v151 offset:2048
	ds_read_b128 v[194:197], v151 offset:3072
	ds_read_b128 v[198:201], v151 offset:4096
	ds_read_b128 v[202:205], v151 offset:5120
	ds_read_b128 v[206:209], v151 offset:6144
	ds_read_b128 v[210:213], v151 offset:7168
	global_load_lds_dwordx4 v[144:145], off
	v_lshl_add_u64 v[144:145], s[26:27], 0, v[134:135]
	s_add_i32 m0, s25, 0xe000
	s_nop 0
	global_load_lds_dwordx4 v[144:145], off
	s_waitcnt vmcnt(8)
	s_waitcnt lgkmcnt(0)
	s_barrier
	s_setprio 1
	s_waitcnt lgkmcnt(0)
	v_mfma_f32_16x16x32_bf16 v[124:127], v[140:143], v[180:183], v[124:127]
	v_mfma_f32_16x16x32_bf16 v[120:123], v[156:159], v[180:183], v[120:123]
	v_mfma_f32_16x16x32_bf16 v[116:119], v[140:143], v[188:191], v[116:119]
	v_mfma_f32_16x16x32_bf16 v[112:115], v[156:159], v[188:191], v[112:115]
	v_mfma_f32_16x16x32_bf16 v[108:111], v[140:143], v[198:201], v[108:111]
	v_mfma_f32_16x16x32_bf16 v[100:103], v[156:159], v[198:201], v[100:103]
	v_mfma_f32_16x16x32_bf16 v[92:95], v[140:143], v[206:209], v[92:95]
	v_mfma_f32_16x16x32_bf16 v[80:83], v[156:159], v[206:209], v[80:83]
	v_mfma_f32_16x16x32_bf16 v[124:127], v[152:155], v[184:187], v[124:127]
	v_mfma_f32_16x16x32_bf16 v[120:123], v[160:163], v[184:187], v[120:123]
	v_mfma_f32_16x16x32_bf16 v[116:119], v[152:155], v[194:197], v[116:119]
	v_mfma_f32_16x16x32_bf16 v[112:115], v[160:163], v[194:197], v[112:115]
	v_mfma_f32_16x16x32_bf16 v[108:111], v[152:155], v[202:205], v[108:111]
	v_mfma_f32_16x16x32_bf16 v[100:103], v[160:163], v[202:205], v[100:103]
	v_mfma_f32_16x16x32_bf16 v[92:95], v[152:155], v[210:213], v[92:95]
	v_mfma_f32_16x16x32_bf16 v[80:83], v[160:163], v[210:213], v[80:83]
	v_mfma_f32_16x16x32_bf16 v[104:107], v[164:167], v[180:183], v[104:107]
	v_mfma_f32_16x16x32_bf16 v[96:99], v[172:175], v[180:183], v[96:99]
	v_mfma_f32_16x16x32_bf16 v[88:91], v[164:167], v[188:191], v[88:91]
	v_mfma_f32_16x16x32_bf16 v[84:87], v[172:175], v[188:191], v[84:87]
	v_mfma_f32_16x16x32_bf16 v[76:79], v[164:167], v[198:201], v[76:79]
	v_mfma_f32_16x16x32_bf16 v[72:75], v[172:175], v[198:201], v[72:75]
	v_mfma_f32_16x16x32_bf16 v[68:71], v[164:167], v[206:209], v[68:71]
	v_mfma_f32_16x16x32_bf16 v[64:67], v[172:175], v[206:209], v[64:67]
	v_mfma_f32_16x16x32_bf16 v[104:107], v[168:171], v[184:187], v[104:107]
	v_mfma_f32_16x16x32_bf16 v[96:99], v[176:179], v[184:187], v[96:99]
	v_mfma_f32_16x16x32_bf16 v[88:91], v[168:171], v[194:197], v[88:91]
	v_mfma_f32_16x16x32_bf16 v[84:87], v[176:179], v[194:197], v[84:87]
	v_mfma_f32_16x16x32_bf16 v[76:79], v[168:171], v[202:205], v[76:79]
	v_mfma_f32_16x16x32_bf16 v[72:75], v[176:179], v[202:205], v[72:75]
	v_mfma_f32_16x16x32_bf16 v[68:71], v[168:171], v[210:213], v[68:71]
	v_mfma_f32_16x16x32_bf16 v[64:67], v[176:179], v[210:213], v[64:67]
	s_setprio 0
	s_barrier
	s_add_i32 s65, s54, s44
	v_lshl_add_u64 v[144:145], s[36:37], 0, v[130:131]
	s_mov_b32 m0, s65
	ds_read_b128 v[180:183], v151 offset:16384
	ds_read_b128 v[184:187], v151 offset:17408
	ds_read_b128 v[188:191], v151 offset:18432
	ds_read_b128 v[194:197], v151 offset:19456
	ds_read_b128 v[198:201], v151 offset:20480
	ds_read_b128 v[202:205], v151 offset:21504
	ds_read_b128 v[206:209], v151 offset:22528
	ds_read_b128 v[210:213], v151 offset:23552
	global_load_lds_dwordx4 v[144:145], off
	s_add_i32 m0, s65, 0x2000
	s_add_u32 s66, s36, 0x100000
	v_lshl_add_u64 v[214:215], s[36:37], 0, v[128:129]
	s_addc_u32 s67, s37, 0
	s_add_i32 s65, s56, s44
	global_load_lds_dwordx4 v[214:215], off
	v_lshl_add_u64 v[216:217], s[66:67], 0, v[130:131]
	s_mov_b32 m0, s65
	v_lshl_add_u64 v[218:219], s[38:39], 0, v[128:129]
	global_load_lds_dwordx4 v[216:217], off
	v_lshl_add_u64 v[216:217], s[66:67], 0, v[128:129]
	s_add_i32 m0, s65, 0x2000
	s_nop 0
	global_load_lds_dwordx4 v[216:217], off
	v_lshl_add_u64 v[216:217], s[38:39], 0, v[130:131]
	s_mov_b32 m0, s25
	s_nop 0
	global_load_lds_dwordx4 v[216:217], off
	s_mov_b32 m0, s46
	s_nop 0
	global_load_lds_dwordx4 v[218:219], off
	s_waitcnt vmcnt(8)
	s_waitcnt lgkmcnt(0)
	s_barrier
; #define PG8_STAGE(bufoff, gbase, voff) do { _Pragma("unroll") for (int _i = 0; _i < 2; ++_i) \
;         __builtin_amdgcn_global_load_lds((const unsigned*)((const char*)(gbase) + (voff)[_i]), (PG8_LAS unsigned*)(lds + (bufoff) + ldsw + _i * 8192), 16, 0, 0); } while (0)
; #define PG8_LDA(dst, b, h) do { _Pragma("unroll") for (int m = 0; m < 4; ++m) _Pragma("unroll") for (int k = 0; k < 2; ++k) dst[m][k] = *(const PG8_LAS bf16x8*)(lds + PG8_SA(b, h) + aoff + m * 2048 + k * 1024); } while (0)
; #define PG8_LDB(dst, b, h) do { _Pragma("unroll") for (int n = 0; n < 2; ++n) _Pragma("unroll") for (int k = 0; k < 2; ++k) dst[n][k] = *(const PG8_LAS bf16x8*)(lds + PG8_SB(b, h) + boff + n * 2048 + k * 1024); } while (0)
; #define PG8_MMA(ai, bj, At, Bt) do { __builtin_amdgcn_s_setprio(1); _Pragma("unroll") for (int m = 0; m < 4; ++m) _Pragma("unroll") for (int n = 0; n < 2; ++n) _Pragma("unroll") for (int k = 0; k < 2; ++k) \
;         acc[ai][bj][m][n] = __builtin_amdgcn_mfma_f32_16x16x32_bf16(Bt[n][k], At[m][k], acc[ai][bj][m][n], 0, 0, 0); __builtin_amdgcn_s_setprio(0); } while (0)
; #define PG8_WAIT_V(n) asm volatile("s_waitcnt vmcnt(" #n ")" ::: "memory")
; #define PG8_WAIT_L(n) asm volatile("s_waitcnt lgkmcnt(" #n ")" ::: "memory")
; #define PG8_BAR __builtin_amdgcn_s_barrier()
; #define PG8_SCHED __builtin_amdgcn_sched_barrier(0)
; template <class Epi, class Sched, bool ALIGN_EPI = false, bool SP2 = false>
; __device__ __forceinline__ void gemm_phase(PG8_LAS unsigned char* lds, const Gemm g, const Sched& S, const Epi& E) {
;     ...
;             PG8_WAIT_V(8); PG8_WAIT_L(0); PG8_BAR; PG8_MMA(1, 0, At, B0); PG8_MMA(1, 1, At, B1); PG8_BAR; PG8_SCHED;
;             PG8_LDB(B0, 1, 0); PG8_LDB(B1, 1, 1); PG8_SCHED; PG8_LDA(At, 1, 0); PG8_STAGE(PG8_SA(0, 1), a2 + hstep, voffA);
;             PG8_WAIT_V(8); PG8_WAIT_L(0); PG8_BAR; PG8_MMA(0, 0, At, B0); PG8_MMA(0, 1, At, B1); PG8_BAR; PG8_SCHED;
	s_setprio 1
	s_waitcnt lgkmcnt(0)
	v_mfma_f32_16x16x32_bf16 v[60:63], v[140:143], v[180:183], v[60:63]
	v_mfma_f32_16x16x32_bf16 v[56:59], v[156:159], v[180:183], v[56:59]
	v_mfma_f32_16x16x32_bf16 v[52:55], v[140:143], v[188:191], v[52:55]
	v_mfma_f32_16x16x32_bf16 v[48:51], v[156:159], v[188:191], v[48:51]
	v_mfma_f32_16x16x32_bf16 v[44:47], v[140:143], v[198:201], v[44:47]
	v_mfma_f32_16x16x32_bf16 v[36:39], v[156:159], v[198:201], v[36:39]
	v_mfma_f32_16x16x32_bf16 v[28:31], v[140:143], v[206:209], v[28:31]
	v_mfma_f32_16x16x32_bf16 v[8:11], v[156:159], v[206:209], v[8:11]
	v_mfma_f32_16x16x32_bf16 v[60:63], v[152:155], v[184:187], v[60:63]
	v_mfma_f32_16x16x32_bf16 v[56:59], v[160:163], v[184:187], v[56:59]
	v_mfma_f32_16x16x32_bf16 v[52:55], v[152:155], v[194:197], v[52:55]
	v_mfma_f32_16x16x32_bf16 v[48:51], v[160:163], v[194:197], v[48:51]
	v_mfma_f32_16x16x32_bf16 v[44:47], v[152:155], v[202:205], v[44:47]
	v_mfma_f32_16x16x32_bf16 v[36:39], v[160:163], v[202:205], v[36:39]
	v_mfma_f32_16x16x32_bf16 v[28:31], v[152:155], v[210:213], v[28:31]
	v_mfma_f32_16x16x32_bf16 v[8:11], v[160:163], v[210:213], v[8:11]
	v_mfma_f32_16x16x32_bf16 v[40:43], v[164:167], v[180:183], v[40:43]
	v_mfma_f32_16x16x32_bf16 v[32:35], v[172:175], v[180:183], v[32:35]
	v_mfma_f32_16x16x32_bf16 v[24:27], v[164:167], v[188:191], v[24:27]
	v_mfma_f32_16x16x32_bf16 v[20:23], v[172:175], v[188:191], v[20:23]
	v_mfma_f32_16x16x32_bf16 v[16:19], v[164:167], v[198:201], v[16:19]
	v_mfma_f32_16x16x32_bf16 v[12:15], v[172:175], v[198:201], v[12:15]
	v_mfma_f32_16x16x32_bf16 v[4:7], v[164:167], v[206:209], v[4:7]
	v_mfma_f32_16x16x32_bf16 v[0:3], v[172:175], v[206:209], v[0:3]
	v_mfma_f32_16x16x32_bf16 v[40:43], v[168:171], v[184:187], v[40:43]
	v_mfma_f32_16x16x32_bf16 v[32:35], v[176:179], v[184:187], v[32:35]
	v_mfma_f32_16x16x32_bf16 v[24:27], v[168:171], v[194:197], v[24:27]
	v_mfma_f32_16x16x32_bf16 v[20:23], v[176:179], v[194:197], v[20:23]
	v_mfma_f32_16x16x32_bf16 v[16:19], v[168:171], v[202:205], v[16:19]
	v_mfma_f32_16x16x32_bf16 v[12:15], v[176:179], v[202:205], v[12:15]
	v_mfma_f32_16x16x32_bf16 v[4:7], v[168:171], v[210:213], v[4:7]
	v_mfma_f32_16x16x32_bf16 v[0:3], v[176:179], v[210:213], v[0:3]
	s_setprio 0
	s_barrier
	s_add_i32 s65, 0, 0x18000
	s_add_i32 s66, 0, 0x1c000
	v_add_u32_e32 v160, s65, v147
	v_add_u32_e32 v176, s66, v147
	ds_read_b128 v[140:143], v160
	ds_read_b128 v[152:155], v160 offset:1024
	ds_read_b128 v[156:159], v160 offset:2048
	ds_read_b128 v[160:163], v160 offset:3072
	ds_read_b128 v[164:167], v176
	ds_read_b128 v[168:171], v176 offset:1024
	ds_read_b128 v[172:175], v176 offset:2048
	ds_read_b128 v[176:179], v176 offset:3072
	s_add_u32 s38, s38, 0x100000
	s_addc_u32 s39, s39, 0
	s_mov_b32 m0, s47
	v_lshl_add_u64 v[220:221], s[38:39], 0, v[130:131]
	ds_read_b128 v[180:183], v151 offset:32768
	ds_read_b128 v[184:187], v151 offset:33792
	ds_read_b128 v[188:191], v151 offset:34816
	ds_read_b128 v[194:197], v151 offset:35840
	ds_read_b128 v[198:201], v151 offset:36864
	ds_read_b128 v[202:205], v151 offset:37888
	ds_read_b128 v[206:209], v151 offset:38912
	ds_read_b128 v[210:213], v151 offset:39936
	global_load_lds_dwordx4 v[220:221], off
	v_lshl_add_u64 v[220:221], s[38:39], 0, v[128:129]
	s_mov_b32 m0, s48
	s_nop 0
	global_load_lds_dwordx4 v[220:221], off
	s_waitcnt vmcnt(8)
	s_waitcnt lgkmcnt(0)
	s_barrier
	s_setprio 1
	s_waitcnt lgkmcnt(0)
	v_mfma_f32_16x16x32_bf16 v[124:127], v[140:143], v[180:183], v[124:127]
	v_mfma_f32_16x16x32_bf16 v[120:123], v[156:159], v[180:183], v[120:123]
	v_mfma_f32_16x16x32_bf16 v[116:119], v[140:143], v[188:191], v[116:119]
	v_mfma_f32_16x16x32_bf16 v[112:115], v[156:159], v[188:191], v[112:115]
	v_mfma_f32_16x16x32_bf16 v[108:111], v[140:143], v[198:201], v[108:111]
	v_mfma_f32_16x16x32_bf16 v[100:103], v[156:159], v[198:201], v[100:103]
	v_mfma_f32_16x16x32_bf16 v[92:95], v[140:143], v[206:209], v[92:95]
	v_mfma_f32_16x16x32_bf16 v[80:83], v[156:159], v[206:209], v[80:83]
	v_mfma_f32_16x16x32_bf16 v[124:127], v[152:155], v[184:187], v[124:127]
	v_mfma_f32_16x16x32_bf16 v[120:123], v[160:163], v[184:187], v[120:123]
	v_mfma_f32_16x16x32_bf16 v[116:119], v[152:155], v[194:197], v[116:119]
	v_mfma_f32_16x16x32_bf16 v[112:115], v[160:163], v[194:197], v[112:115]
	v_mfma_f32_16x16x32_bf16 v[108:111], v[152:155], v[202:205], v[108:111]
	v_mfma_f32_16x16x32_bf16 v[100:103], v[160:163], v[202:205], v[100:103]
	v_mfma_f32_16x16x32_bf16 v[92:95], v[152:155], v[210:213], v[92:95]
	v_mfma_f32_16x16x32_bf16 v[80:83], v[160:163], v[210:213], v[80:83]
	v_mfma_f32_16x16x32_bf16 v[104:107], v[164:167], v[180:183], v[104:107]
	v_mfma_f32_16x16x32_bf16 v[96:99], v[172:175], v[180:183], v[96:99]
	v_mfma_f32_16x16x32_bf16 v[88:91], v[164:167], v[188:191], v[88:91]
	v_mfma_f32_16x16x32_bf16 v[84:87], v[172:175], v[188:191], v[84:87]
	v_mfma_f32_16x16x32_bf16 v[76:79], v[164:167], v[198:201], v[76:79]
	v_mfma_f32_16x16x32_bf16 v[72:75], v[172:175], v[198:201], v[72:75]
	v_mfma_f32_16x16x32_bf16 v[68:71], v[164:167], v[206:209], v[68:71]
	v_mfma_f32_16x16x32_bf16 v[64:67], v[172:175], v[206:209], v[64:67]
	v_mfma_f32_16x16x32_bf16 v[104:107], v[168:171], v[184:187], v[104:107]
	v_mfma_f32_16x16x32_bf16 v[96:99], v[176:179], v[184:187], v[96:99]
	v_mfma_f32_16x16x32_bf16 v[88:91], v[168:171], v[194:197], v[88:91]
	v_mfma_f32_16x16x32_bf16 v[84:87], v[176:179], v[194:197], v[84:87]
	v_mfma_f32_16x16x32_bf16 v[76:79], v[168:171], v[202:205], v[76:79]
	v_mfma_f32_16x16x32_bf16 v[72:75], v[176:179], v[202:205], v[72:75]
	v_mfma_f32_16x16x32_bf16 v[68:71], v[168:171], v[210:213], v[68:71]
	v_mfma_f32_16x16x32_bf16 v[64:67], v[176:179], v[210:213], v[64:67]
	s_setprio 0
	s_barrier
; #define PG8_STAGE(bufoff, gbase, voff) do { _Pragma("unroll") for (int _i = 0; _i < 2; ++_i) \
;         __builtin_amdgcn_global_load_lds((const unsigned*)((const char*)(gbase) + (voff)[_i]), (PG8_LAS unsigned*)(lds + (bufoff) + ldsw + _i * 8192), 16, 0, 0); } while (0)
; #define PG8_LDA(dst, b, h) do { _Pragma("unroll") for (int m = 0; m < 4; ++m) _Pragma("unroll") for (int k = 0; k < 2; ++k) dst[m][k] = *(const PG8_LAS bf16x8*)(lds + PG8_SA(b, h) + aoff + m * 2048 + k * 1024); } while (0)
; #define PG8_MMA(ai, bj, At, Bt) do { __builtin_amdgcn_s_setprio(1); _Pragma("unroll") for (int m = 0; m < 4; ++m) _Pragma("unroll") for (int n = 0; n < 2; ++n) _Pragma("unroll") for (int k = 0; k < 2; ++k) \
;         acc[ai][bj][m][n] = __builtin_amdgcn_mfma_f32_16x16x32_bf16(Bt[n][k], At[m][k], acc[ai][bj][m][n], 0, 0, 0); __builtin_amdgcn_s_setprio(0); } while (0)
; #define PG8_WAIT_V(n) asm volatile("s_waitcnt vmcnt(" #n ")" ::: "memory")
; #define PG8_WAIT_L(n) asm volatile("s_waitcnt lgkmcnt(" #n ")" ::: "memory")
; #define PG8_BAR __builtin_amdgcn_s_barrier()
; #define PG8_SCHED __builtin_amdgcn_sched_barrier(0)
; template <class Epi, class Sched, bool ALIGN_EPI = false, bool SP2 = false>
; __device__ __forceinline__ void gemm_phase(PG8_LAS unsigned char* lds, const Gemm g, const Sched& S, const Epi& E) {
;     ...
;         for (int t = 0; t < nt; t += 2) {
;             const bool last = (t == nt - 2);
;             const char* a1 = cA + (size_t)(t + 1) * kstep;
;             const char* a2 = last ? nA : cA + (size_t)(t + 2) * kstep; const char* b2 = last ? nB : cB + (size_t)(t + 2) * kstep;
;     ...
;             PG8_LDA(At, 1, 1); PG8_STAGE(PG8_SB(1, 0), b3, voffB); PG8_STAGE(PG8_SB(1, 1), b3 + hstep, voffB); PG8_STAGE(PG8_SA(1, 0), a3, voffA);
;             PG8_WAIT_V(8); PG8_WAIT_L(0); PG8_BAR; PG8_MMA(1, 0, At, B0); PG8_MMA(1, 1, At, B1); PG8_BAR; PG8_SCHED;
	s_add_i32 s38, s65, s44
	v_lshl_add_u64 v[144:145], v[144:145], 0, s[12:13]
	s_mov_b32 m0, s38
	ds_read_b128 v[180:183], v151 offset:49152
	ds_read_b128 v[184:187], v151 offset:50176
	ds_read_b128 v[188:191], v151 offset:51200
	ds_read_b128 v[194:197], v151 offset:52224
	ds_read_b128 v[198:201], v151 offset:53248
	ds_read_b128 v[202:205], v151 offset:54272
	ds_read_b128 v[206:209], v151 offset:55296
	ds_read_b128 v[210:213], v151 offset:56320
	global_load_lds_dwordx4 v[144:145], off
	s_add_i32 m0, s38, 0x2000
	s_add_u32 s36, s36, 0x100080
	v_lshl_add_u64 v[144:145], v[214:215], 0, s[12:13]
	s_addc_u32 s37, s37, 0
	s_add_i32 s38, s66, s44
	global_load_lds_dwordx4 v[144:145], off
	v_lshl_add_u64 v[144:145], s[36:37], 0, v[130:131]
	s_mov_b32 m0, s38
	s_nop 0
	global_load_lds_dwordx4 v[144:145], off
	v_lshl_add_u64 v[144:145], s[36:37], 0, v[128:129]
	s_add_i32 m0, s38, 0x2000
	s_nop 0
	global_load_lds_dwordx4 v[144:145], off
	v_lshl_add_u64 v[144:145], v[216:217], 0, s[12:13]
	s_mov_b32 m0, s51
	s_nop 0
	global_load_lds_dwordx4 v[144:145], off
	v_lshl_add_u64 v[144:145], v[218:219], 0, s[12:13]
	s_mov_b32 m0, s52
	s_nop 0
	global_load_lds_dwordx4 v[144:145], off
	s_waitcnt vmcnt(8)
	s_waitcnt lgkmcnt(0)
	s_barrier
	s_setprio 1
	s_waitcnt lgkmcnt(0)
	v_mfma_f32_16x16x32_bf16 v[60:63], v[140:143], v[180:183], v[60:63]
	v_mfma_f32_16x16x32_bf16 v[56:59], v[156:159], v[180:183], v[56:59]
	v_mfma_f32_16x16x32_bf16 v[52:55], v[140:143], v[188:191], v[52:55]
	v_mfma_f32_16x16x32_bf16 v[48:51], v[156:159], v[188:191], v[48:51]
	v_mfma_f32_16x16x32_bf16 v[44:47], v[140:143], v[198:201], v[44:47]
	v_mfma_f32_16x16x32_bf16 v[36:39], v[156:159], v[198:201], v[36:39]
	v_mfma_f32_16x16x32_bf16 v[28:31], v[140:143], v[206:209], v[28:31]
	v_mfma_f32_16x16x32_bf16 v[8:11], v[156:159], v[206:209], v[8:11]
	v_mfma_f32_16x16x32_bf16 v[60:63], v[152:155], v[184:187], v[60:63]
	v_mfma_f32_16x16x32_bf16 v[56:59], v[160:163], v[184:187], v[56:59]
	v_mfma_f32_16x16x32_bf16 v[52:55], v[152:155], v[194:197], v[52:55]
	v_mfma_f32_16x16x32_bf16 v[48:51], v[160:163], v[194:197], v[48:51]
	v_mfma_f32_16x16x32_bf16 v[44:47], v[152:155], v[202:205], v[44:47]
	v_mfma_f32_16x16x32_bf16 v[36:39], v[160:163], v[202:205], v[36:39]
	v_mfma_f32_16x16x32_bf16 v[28:31], v[152:155], v[210:213], v[28:31]
	v_mfma_f32_16x16x32_bf16 v[8:11], v[160:163], v[210:213], v[8:11]
	v_mfma_f32_16x16x32_bf16 v[40:43], v[164:167], v[180:183], v[40:43]
	v_mfma_f32_16x16x32_bf16 v[32:35], v[172:175], v[180:183], v[32:35]
	v_mfma_f32_16x16x32_bf16 v[24:27], v[164:167], v[188:191], v[24:27]
	v_mfma_f32_16x16x32_bf16 v[20:23], v[172:175], v[188:191], v[20:23]
	v_mfma_f32_16x16x32_bf16 v[16:19], v[164:167], v[198:201], v[16:19]
	v_mfma_f32_16x16x32_bf16 v[12:15], v[172:175], v[198:201], v[12:15]
	v_mfma_f32_16x16x32_bf16 v[4:7], v[164:167], v[206:209], v[4:7]
	v_mfma_f32_16x16x32_bf16 v[0:3], v[172:175], v[206:209], v[0:3]
	v_mfma_f32_16x16x32_bf16 v[40:43], v[168:171], v[184:187], v[40:43]
	v_mfma_f32_16x16x32_bf16 v[32:35], v[176:179], v[184:187], v[32:35]
	v_mfma_f32_16x16x32_bf16 v[24:27], v[168:171], v[194:197], v[24:27]
	v_mfma_f32_16x16x32_bf16 v[20:23], v[176:179], v[194:197], v[20:23]
	v_mfma_f32_16x16x32_bf16 v[16:19], v[168:171], v[202:205], v[16:19]
	v_mfma_f32_16x16x32_bf16 v[12:15], v[176:179], v[202:205], v[12:15]
	v_mfma_f32_16x16x32_bf16 v[4:7], v[168:171], v[210:213], v[4:7]
	v_mfma_f32_16x16x32_bf16 v[0:3], v[176:179], v[210:213], v[0:3]
	s_setprio 0
	s_barrier
	s_add_i32 s64, s64, 2
	s_add_u32 s26, s26, 0x100
	s_addc_u32 s27, s27, 0
	s_add_u32 s62, s62, 0x100
	s_addc_u32 s63, s63, 0
	s_cmp_gt_u32 s64, 61
	s_cbranch_scc0 .LBB0_1224
	s_and_b64 vcc, exec, s[14:15]
	s_cbranch_vccz .LBB0_1227
	s_barrier
